# MLA loop: second tile of each barrier interval issues its LDS store / reload pieces four MFMA slots earlier (slots 10-12)
# speedup vs baseline: 1.0033x; 1.0033x over previous
; template <int VAR>
; __device__ __forceinline__ void attn_phase(LAS unsigned char* lds, const AttnP P, int vcu, int G, int wave_s) {
;     ...
;                 if (ND0 == 6) {
;                     KR1(0); KR1(1); KR1(2); KR1(3); SB();
;                     QK1(0, negm); EX2(pc0, 0, w0.x); KR1(4); SB();
;                     QK1(1, negm); EX2(pc0, 2, w0.y); KR1(5); SB();
;                     QK1(2, pn0); EX2(pc0, 4, w0.z); KR1(6); SB();
;                     QK1(3, pn1); EX2(pc0, 6, w0.w); KR1(7); SB();
;                     QK1(4, pn0); EX2(pc0, 8, w1.x); KR1(8); SB();
;                     QK1(5, pn1); EX2(pc0, 10, w1.y); KR1(9); SB();
;                     QK1(6, pn0); EX2(pc0, 12, w1.z); KR1(10); SB();
;                     QK1(7, pn1); EX2(pc0, 14, w1.w); KR1(11); SB();
;                     QK1(8, pn0); EX2(pc1, 0, w2.x); VR1(0); SB();
;                     QK1(9, pn1); EX2(pc1, 2, w2.y); VR1(1); SB();
;                     QK1(10, pn0); EX2(pc1, 4, w2.z); VR1(2); SB();
;                     QK1(11, pn1); EX2(pc1, 6, w2.w); VR1(3); SB();
;                 } else {
;                     KR1(0); KR1(1); KR1(2); KR1(3); SB();
;                     QK1(0, negm); EX2(pc0, 0, w0.x); EX2(pc0, 2, w0.y); KR1(4); SB();
;                     QK1(1, negm); EX2(pc0, 4, w0.z); EX2(pc0, 6, w0.w); KR1(5); SB();
;                     QK1(2, pn0); EX2(pc0, 8, w1.x); EX2(pc0, 10, w1.y); KR1(6); SB();
;                     QK1(3, pn1); EX2(pc0, 12, w1.z); EX2(pc0, 14, w1.w); KR1(7); SB();
;                     QK1(4, pn0); EX2(pc1, 0, w2.x); VR1(0); SB();
;                     QK1(5, pn1); EX2(pc1, 2, w2.y); VR1(1); SB();
;                     QK1(6, pn0); EX2(pc1, 4, w2.z); VR1(2); SB();
;                     QK1(7, pn1); EX2(pc1, 6, w2.w); VR1(3); SB();
;                 }
;                 PV1(0, w0); EX2(pc1, 8, w3.x); VR1(4); SB();
;                 PV1(1, w0); EX2(pc1, 10, w3.y); VR1(5); SB();
;                 PV1(2, w1); EX2(pc1, 12, w3.z); VR1(6); SB();
;                 PV1(3, w1); EX2(pc1, 14, w3.w); VR1(7); SB();
;                 lrun += sacc;
;                 PV1(4, w2); MASK_TILE(pn0, pn1, t + 1); SB();
;                 PV1(5, w2); SB();
;                 PV1(6, w3); SB();
;                 PV1(7, w3); rmn = rowmax32(pn0, pn1); if (!USE_NEGM) rmn -= mref; SB();
;     ...
;             if (hn) { STOREK(t & 1); STOREV((t + 1) & 1); }
;             __syncthreads();
.Lmla_p1_go:
	v_exp_f32_e32 v222, v82
	v_exp_f32_e32 v223, v83
	v_add_f32_e32 v164, 0, v222
	v_cvt_pk_bf16_f32 v206, v222, v223
	v_add_f32_e32 v164, v223, v164
	v_exp_f32_e32 v224, v84
	v_exp_f32_e32 v225, v85
	v_add_f32_e32 v164, v224, v164
	v_cvt_pk_bf16_f32 v207, v224, v225
	v_add_f32_e32 v164, v225, v164
	s_waitcnt lgkmcnt(4)
	v_mfma_f32_32x32x16_bf16 v[34:49], v[182:185], v[114:117], v[66:81]
	ds_read_b128 v[198:201], v174 offset:45120
	v_exp_f32_e32 v222, v86
	v_exp_f32_e32 v223, v87
	v_add_f32_e32 v164, v222, v164
	v_cvt_pk_bf16_f32 v208, v222, v223
	v_add_f32_e32 v164, v223, v164
	s_waitcnt lgkmcnt(4)
	v_mfma_f32_32x32x16_bf16 v[50:65], v[186:189], v[114:117], v[66:81]
	ds_read_b128 v[182:185], v174 offset:51776
	v_exp_f32_e32 v224, v88
	v_exp_f32_e32 v225, v89
	v_add_f32_e32 v164, v224, v164
	v_cvt_pk_bf16_f32 v209, v224, v225
	v_add_f32_e32 v164, v225, v164
	s_waitcnt lgkmcnt(3)
	v_mfma_f32_32x32x16_bf16 v[34:49], v[190:193], v[118:121], v[34:49]
	ds_read_b128 v[186:189], v174 offset:45152
	v_exp_f32_e32 v222, v90
	v_exp_f32_e32 v223, v91
	v_add_f32_e32 v164, v222, v164
	v_cvt_pk_bf16_f32 v210, v222, v223
	v_add_f32_e32 v164, v223, v164
	s_waitcnt lgkmcnt(3)
	v_mfma_f32_32x32x16_bf16 v[50:65], v[194:197], v[118:121], v[50:65]
	ds_read_b128 v[190:193], v174 offset:51808
	v_exp_f32_e32 v224, v92
	v_exp_f32_e32 v225, v93
	v_add_f32_e32 v164, v224, v164
	v_cvt_pk_bf16_f32 v211, v224, v225
	v_add_f32_e32 v164, v225, v164
	s_waitcnt lgkmcnt(3)
	v_mfma_f32_32x32x16_bf16 v[34:49], v[198:201], v[122:125], v[34:49]
	ds_read_b128 v[194:197], v174 offset:45184
	v_exp_f32_e32 v222, v94
	v_exp_f32_e32 v223, v95
	v_add_f32_e32 v164, v222, v164
	v_cvt_pk_bf16_f32 v212, v222, v223
	v_add_f32_e32 v164, v223, v164
	s_waitcnt lgkmcnt(3)
	v_mfma_f32_32x32x16_bf16 v[50:65], v[182:185], v[122:125], v[50:65]
	ds_read_b128 v[198:201], v174 offset:51840
	v_exp_f32_e32 v224, v96
	v_exp_f32_e32 v225, v97
	v_add_f32_e32 v164, v224, v164
	v_cvt_pk_bf16_f32 v213, v224, v225
	v_add_f32_e32 v164, v225, v164
	s_waitcnt lgkmcnt(3)
	v_mfma_f32_32x32x16_bf16 v[34:49], v[186:189], v[126:129], v[34:49]
	ds_read_b128 v[182:185], v174 offset:45216
	v_exp_f32_e32 v222, v98
	v_exp_f32_e32 v223, v99
	v_add_f32_e32 v164, v222, v164
	v_cvt_pk_bf16_f32 v214, v222, v223
	v_add_f32_e32 v164, v223, v164
	s_waitcnt lgkmcnt(3)
	v_mfma_f32_32x32x16_bf16 v[50:65], v[190:193], v[126:129], v[50:65]
	ds_read_b128 v[186:189], v174 offset:51872
	v_exp_f32_e32 v224, v100
	v_exp_f32_e32 v225, v101
	v_add_f32_e32 v164, v224, v164
	v_cvt_pk_bf16_f32 v215, v224, v225
	v_add_f32_e32 v164, v225, v164
	s_waitcnt lgkmcnt(3)
	v_mfma_f32_32x32x16_bf16 v[34:49], v[194:197], v[130:133], v[34:49]
	ds_read_b128 v[190:193], v228 offset:35840
	v_exp_f32_e32 v222, v102
	v_exp_f32_e32 v223, v103
	v_add_f32_e32 v164, v222, v164
	v_cvt_pk_bf16_f32 v216, v222, v223
	v_add_f32_e32 v164, v223, v164
	s_waitcnt lgkmcnt(3)
	v_mfma_f32_32x32x16_bf16 v[50:65], v[198:201], v[130:133], v[50:65]
	ds_read_b128 v[194:197], v228 offset:40448
	v_exp_f32_e32 v224, v104
	v_exp_f32_e32 v225, v105
	v_add_f32_e32 v164, v224, v164
	v_cvt_pk_bf16_f32 v217, v224, v225
	v_add_f32_e32 v164, v225, v164
	s_mov_b32 s13, s20
	s_mov_b32 s20, s19
	s_add_i32 s19, s19, 1
	s_cmp_eq_u32 s19, s9
	s_cselect_b32 s19, 0, s19
	s_waitcnt lgkmcnt(3)
	v_mfma_f32_32x32x16_bf16 v[34:49], v[182:185], v[134:137], v[34:49]
	ds_read_b128 v[198:201], v228 offset:35872
	v_exp_f32_e32 v222, v106
	v_exp_f32_e32 v223, v107
	v_add_f32_e32 v164, v222, v164
	v_cvt_pk_bf16_f32 v218, v222, v223
	v_add_f32_e32 v164, v223, v164
	s_waitcnt vmcnt(2)
	ds_write_b128 v172, v[150:153]
	v_lshl_add_u32 v222, s19, 17, v178
	global_load_dwordx4 v[150:153], v222, s[52:53]
	s_waitcnt lgkmcnt(4)
	v_mfma_f32_32x32x16_bf16 v[50:65], v[186:189], v[134:137], v[50:65]
	ds_read_b128 v[182:185], v228 offset:40480
	v_exp_f32_e32 v224, v108
	v_exp_f32_e32 v225, v109
	v_add_f32_e32 v164, v224, v164
	v_cvt_pk_bf16_f32 v219, v224, v225
	v_add_f32_e32 v164, v225, v164
	s_and_b64 vcc, exec, s[2:3]
	s_cbranch_vccz .Lmla_p1_nope
	ds_write_b128 v176, v[160:163] offset:128
	v_lshl_add_u32 v222, s19, 12, v179
	global_load_dwordx4 v[160:163], v222, s[62:63]
.Lmla_p1_nope:
	s_waitcnt lgkmcnt(4)
	v_mfma_f32_32x32x16_bf16 v[2:17], v[190:193], v[206:209], v[2:17]
	ds_read_b128 v[186:189], v228 offset:35904
	v_exp_f32_e32 v222, v110
	v_exp_f32_e32 v223, v111
	v_add_f32_e32 v164, v222, v164
	v_cvt_pk_bf16_f32 v220, v222, v223
	v_add_f32_e32 v164, v223, v164
	v_add_u32_e32 v222, 0xb000, v173
	ds_write_b128 v222, v[202:205] offset:49152
	v_lshl_add_u32 v222, s13, 7, v168
	global_load_dwordx4 v[202:205], v222, s[56:57]
	s_waitcnt lgkmcnt(5)
	v_mfma_f32_32x32x16_bf16 v[18:33], v[194:197], v[206:209], v[18:33]
	ds_read_b128 v[190:193], v228 offset:40512
	v_exp_f32_e32 v224, v112
	v_exp_f32_e32 v225, v113
	v_add_f32_e32 v164, v224, v164
	v_cvt_pk_bf16_f32 v221, v224, v225
	v_add_f32_e32 v164, v225, v164
	s_waitcnt lgkmcnt(5)
	v_mfma_f32_32x32x16_bf16 v[2:17], v[198:201], v[210:213], v[2:17]
	ds_read_b128 v[194:197], v228 offset:35936
	v_max3_f32 v224, v34, v35, v36
	v_max3_f32 v225, v50, v51, v52
	v_max3_f32 v224, v224, v37, v38
	v_max3_f32 v225, v225, v53, v54
	s_waitcnt lgkmcnt(4)
	v_mfma_f32_32x32x16_bf16 v[18:33], v[182:185], v[210:213], v[18:33]
	ds_read_b128 v[198:201], v228 offset:40544
	ds_read_b128 v[182:185], v229 offset:13312
	v_max3_f32 v224, v224, v39, v40
	v_max3_f32 v225, v225, v55, v56
	v_max3_f32 v224, v224, v41, v42
	v_max3_f32 v225, v225, v57, v58
	s_waitcnt lgkmcnt(5)
	v_mfma_f32_32x32x16_bf16 v[2:17], v[186:189], v[214:217], v[2:17]
	ds_read_b128 v[186:189], v229 offset:19968
	v_max3_f32 v224, v224, v43, v44
	v_max3_f32 v225, v225, v59, v60
	v_max3_f32 v224, v224, v45, v46
	v_max3_f32 v225, v225, v61, v62
	s_waitcnt lgkmcnt(4)
	v_mfma_f32_32x32x16_bf16 v[18:33], v[190:193], v[214:217], v[18:33]
	ds_read_b128 v[190:193], v229 offset:13344
	v_max3_f32 v224, v224, v47, v48
	v_max3_f32 v225, v225, v63, v64
	v_max3_f32 v224, v224, v49, v65
	v_max_f32_e32 v224, v224, v225
	s_waitcnt lgkmcnt(4)
	v_mfma_f32_32x32x16_bf16 v[2:17], v[194:197], v[218:221], v[2:17]
	ds_read_b128 v[194:197], v229 offset:20000
	v_mov_b32_e32 v225, v224
	v_add_f32_e32 v1, v1, v164
	s_add_i32 s11, s11, 1
	v_permlane32_swap_b32_e32 v224, v225
	s_cmp_eq_u32 s9, s11
	v_max_f32_e32 v167, v224, v225
	v_cmp_lt_f32_e32 vcc, s66, v167
	s_waitcnt lgkmcnt(4)
	v_mfma_f32_32x32x16_bf16 v[18:33], v[198:201], v[218:221], v[18:33]
	s_waitcnt lgkmcnt(7)
	s_barrier

; template <int VAR>
; __device__ __forceinline__ void attn_phase(LAS unsigned char* lds, const AttnP P, int vcu, int G, int wave_s) {
;     ...
;                 if (ND0 == 6) {
;                     KR1(0); KR1(1); KR1(2); KR1(3); SB();
;                     QK1(0, negm); EX2(pc0, 0, w0.x); KR1(4); SB();
;                     QK1(1, negm); EX2(pc0, 2, w0.y); KR1(5); SB();
;                     QK1(2, pn0); EX2(pc0, 4, w0.z); KR1(6); SB();
;                     QK1(3, pn1); EX2(pc0, 6, w0.w); KR1(7); SB();
;                     QK1(4, pn0); EX2(pc0, 8, w1.x); KR1(8); SB();
;                     QK1(5, pn1); EX2(pc0, 10, w1.y); KR1(9); SB();
;                     QK1(6, pn0); EX2(pc0, 12, w1.z); KR1(10); SB();
;                     QK1(7, pn1); EX2(pc0, 14, w1.w); KR1(11); SB();
;                     QK1(8, pn0); EX2(pc1, 0, w2.x); VR1(0); SB();
;                     QK1(9, pn1); EX2(pc1, 2, w2.y); VR1(1); SB();
;                     QK1(10, pn0); EX2(pc1, 4, w2.z); VR1(2); SB();
;                     QK1(11, pn1); EX2(pc1, 6, w2.w); VR1(3); SB();
;                 } else {
;                     KR1(0); KR1(1); KR1(2); KR1(3); SB();
;                     QK1(0, negm); EX2(pc0, 0, w0.x); EX2(pc0, 2, w0.y); KR1(4); SB();
;                     QK1(1, negm); EX2(pc0, 4, w0.z); EX2(pc0, 6, w0.w); KR1(5); SB();
;                     QK1(2, pn0); EX2(pc0, 8, w1.x); EX2(pc0, 10, w1.y); KR1(6); SB();
;                     QK1(3, pn1); EX2(pc0, 12, w1.z); EX2(pc0, 14, w1.w); KR1(7); SB();
;                     QK1(4, pn0); EX2(pc1, 0, w2.x); VR1(0); SB();
;                     QK1(5, pn1); EX2(pc1, 2, w2.y); VR1(1); SB();
;                     QK1(6, pn0); EX2(pc1, 4, w2.z); VR1(2); SB();
;                     QK1(7, pn1); EX2(pc1, 6, w2.w); VR1(3); SB();
;                 }
;                 PV1(0, w0); EX2(pc1, 8, w3.x); VR1(4); SB();
;                 PV1(1, w0); EX2(pc1, 10, w3.y); VR1(5); SB();
;                 PV1(2, w1); EX2(pc1, 12, w3.z); VR1(6); SB();
;                 PV1(3, w1); EX2(pc1, 14, w3.w); VR1(7); SB();
;                 lrun += sacc;
;                 PV1(4, w2); MASK_TILE(pn0, pn1, t + 1); SB();
;                 PV1(5, w2); SB();
;                 PV1(6, w3); SB();
;                 PV1(7, w3); rmn = rowmax32(pn0, pn1); if (!USE_NEGM) rmn -= mref; SB();
;     ...
;             if (hn) { STOREK(t & 1); STOREV((t + 1) & 1); }
;             __syncthreads();
.Lmla_p3_go:
	v_exp_f32_e32 v222, v82
	v_exp_f32_e32 v223, v83
	v_add_f32_e32 v164, 0, v222
	v_cvt_pk_bf16_f32 v206, v222, v223
	v_add_f32_e32 v164, v223, v164
	v_exp_f32_e32 v224, v84
	v_exp_f32_e32 v225, v85
	v_add_f32_e32 v164, v224, v164
	v_cvt_pk_bf16_f32 v207, v224, v225
	v_add_f32_e32 v164, v225, v164
	s_waitcnt lgkmcnt(4)
	v_mfma_f32_32x32x16_bf16 v[34:49], v[182:185], v[114:117], v[66:81]
	ds_read_b128 v[198:201], v229 offset:26688
	v_exp_f32_e32 v222, v86
	v_exp_f32_e32 v223, v87
	v_add_f32_e32 v164, v222, v164
	v_cvt_pk_bf16_f32 v208, v222, v223
	v_add_f32_e32 v164, v223, v164
	s_waitcnt lgkmcnt(4)
	v_mfma_f32_32x32x16_bf16 v[50:65], v[186:189], v[114:117], v[66:81]
	ds_read_b128 v[182:185], v229 offset:33344
	v_exp_f32_e32 v224, v88
	v_exp_f32_e32 v225, v89
	v_add_f32_e32 v164, v224, v164
	v_cvt_pk_bf16_f32 v209, v224, v225
	v_add_f32_e32 v164, v225, v164
	s_waitcnt lgkmcnt(3)
	v_mfma_f32_32x32x16_bf16 v[34:49], v[190:193], v[118:121], v[34:49]
	ds_read_b128 v[186:189], v229 offset:26720
	v_exp_f32_e32 v222, v90
	v_exp_f32_e32 v223, v91
	v_add_f32_e32 v164, v222, v164
	v_cvt_pk_bf16_f32 v210, v222, v223
	v_add_f32_e32 v164, v223, v164
	s_waitcnt lgkmcnt(3)
	v_mfma_f32_32x32x16_bf16 v[50:65], v[194:197], v[118:121], v[50:65]
	ds_read_b128 v[190:193], v229 offset:33376
	v_exp_f32_e32 v224, v92
	v_exp_f32_e32 v225, v93
	v_add_f32_e32 v164, v224, v164
	v_cvt_pk_bf16_f32 v211, v224, v225
	v_add_f32_e32 v164, v225, v164
	s_waitcnt lgkmcnt(3)
	v_mfma_f32_32x32x16_bf16 v[34:49], v[198:201], v[122:125], v[34:49]
	ds_read_b128 v[194:197], v229 offset:26752
	v_exp_f32_e32 v222, v94
	v_exp_f32_e32 v223, v95
	v_add_f32_e32 v164, v222, v164
	v_cvt_pk_bf16_f32 v212, v222, v223
	v_add_f32_e32 v164, v223, v164
	s_waitcnt lgkmcnt(3)
	v_mfma_f32_32x32x16_bf16 v[50:65], v[182:185], v[122:125], v[50:65]
	ds_read_b128 v[198:201], v229 offset:33408
	v_exp_f32_e32 v224, v96
	v_exp_f32_e32 v225, v97
	v_add_f32_e32 v164, v224, v164
	v_cvt_pk_bf16_f32 v213, v224, v225
	v_add_f32_e32 v164, v225, v164
	s_waitcnt lgkmcnt(3)
	v_mfma_f32_32x32x16_bf16 v[34:49], v[186:189], v[126:129], v[34:49]
	ds_read_b128 v[182:185], v229 offset:26784
	v_exp_f32_e32 v222, v98
	v_exp_f32_e32 v223, v99
	v_add_f32_e32 v164, v222, v164
	v_cvt_pk_bf16_f32 v214, v222, v223
	v_add_f32_e32 v164, v223, v164
	s_waitcnt lgkmcnt(3)
	v_mfma_f32_32x32x16_bf16 v[50:65], v[190:193], v[126:129], v[50:65]
	ds_read_b128 v[186:189], v229 offset:33440
	v_exp_f32_e32 v224, v100
	v_exp_f32_e32 v225, v101
	v_add_f32_e32 v164, v224, v164
	v_cvt_pk_bf16_f32 v215, v224, v225
	v_add_f32_e32 v164, v225, v164
	s_waitcnt lgkmcnt(3)
	v_mfma_f32_32x32x16_bf16 v[34:49], v[194:197], v[130:133], v[34:49]
	ds_read_b128 v[190:193], v181 offset:49152
	v_exp_f32_e32 v222, v102
	v_exp_f32_e32 v223, v103
	v_add_f32_e32 v164, v222, v164
	v_cvt_pk_bf16_f32 v216, v222, v223
	v_add_f32_e32 v164, v223, v164
	s_waitcnt lgkmcnt(3)
	v_mfma_f32_32x32x16_bf16 v[50:65], v[198:201], v[130:133], v[50:65]
	ds_read_b128 v[194:197], v181 offset:53760
	v_exp_f32_e32 v224, v104
	v_exp_f32_e32 v225, v105
	v_add_f32_e32 v164, v224, v164
	v_cvt_pk_bf16_f32 v217, v224, v225
	v_add_f32_e32 v164, v225, v164
	s_mov_b32 s13, s20
	s_mov_b32 s20, s19
	s_add_i32 s19, s19, 1
	s_cmp_eq_u32 s19, s9
	s_cselect_b32 s19, 0, s19
	s_waitcnt lgkmcnt(3)
	v_mfma_f32_32x32x16_bf16 v[34:49], v[182:185], v[134:137], v[34:49]
	ds_read_b128 v[198:201], v181 offset:49184
	v_exp_f32_e32 v222, v106
	v_exp_f32_e32 v223, v107
	v_add_f32_e32 v164, v222, v164
	v_cvt_pk_bf16_f32 v218, v222, v223
	v_add_f32_e32 v164, v223, v164
	s_waitcnt vmcnt(2)
	ds_write_b128 v172, v[150:153] offset:45056
	v_lshl_add_u32 v222, s19, 17, v178
	global_load_dwordx4 v[150:153], v222, s[52:53]
	s_waitcnt lgkmcnt(4)
	v_mfma_f32_32x32x16_bf16 v[50:65], v[186:189], v[134:137], v[50:65]
	ds_read_b128 v[182:185], v181 offset:53792
	v_exp_f32_e32 v224, v108
	v_exp_f32_e32 v225, v109
	v_add_f32_e32 v164, v224, v164
	v_cvt_pk_bf16_f32 v219, v224, v225
	v_add_f32_e32 v164, v225, v164
	s_and_b64 vcc, exec, s[2:3]
	s_cbranch_vccz .Lmla_p3_nope
	ds_write_b128 v176, v[160:163] offset:45184
	v_lshl_add_u32 v222, s19, 12, v179
	global_load_dwordx4 v[160:163], v222, s[62:63]
.Lmla_p3_nope:
	s_waitcnt lgkmcnt(4)
	v_mfma_f32_32x32x16_bf16 v[2:17], v[190:193], v[206:209], v[2:17]
	ds_read_b128 v[186:189], v181 offset:49216
	v_exp_f32_e32 v222, v110
	v_exp_f32_e32 v223, v111
	v_add_f32_e32 v164, v222, v164
	v_cvt_pk_bf16_f32 v220, v222, v223
	v_add_f32_e32 v164, v223, v164
	ds_write_b128 v173, v[202:205] offset:35840
	v_lshl_add_u32 v222, s13, 7, v168
	global_load_dwordx4 v[202:205], v222, s[56:57]
	s_waitcnt lgkmcnt(5)
	v_mfma_f32_32x32x16_bf16 v[18:33], v[194:197], v[206:209], v[18:33]
	ds_read_b128 v[190:193], v181 offset:53824
	v_exp_f32_e32 v224, v112
	v_exp_f32_e32 v225, v113
	v_add_f32_e32 v164, v224, v164
	v_cvt_pk_bf16_f32 v221, v224, v225
	v_add_f32_e32 v164, v225, v164
	s_waitcnt lgkmcnt(5)
	v_mfma_f32_32x32x16_bf16 v[2:17], v[198:201], v[210:213], v[2:17]
	ds_read_b128 v[194:197], v181 offset:49248
	v_max3_f32 v224, v34, v35, v36
	v_max3_f32 v225, v50, v51, v52
	v_max3_f32 v224, v224, v37, v38
	v_max3_f32 v225, v225, v53, v54
	s_waitcnt lgkmcnt(4)
	v_mfma_f32_32x32x16_bf16 v[18:33], v[182:185], v[210:213], v[18:33]
	ds_read_b128 v[198:201], v181 offset:53856
	ds_read_b128 v[182:185], v174
	v_max3_f32 v224, v224, v39, v40
	v_max3_f32 v225, v225, v55, v56
	v_max3_f32 v224, v224, v41, v42
	v_max3_f32 v225, v225, v57, v58
	s_waitcnt lgkmcnt(5)
	v_mfma_f32_32x32x16_bf16 v[2:17], v[186:189], v[214:217], v[2:17]
	ds_read_b128 v[186:189], v174 offset:6656
	v_max3_f32 v224, v224, v43, v44
	v_max3_f32 v225, v225, v59, v60
	v_max3_f32 v224, v224, v45, v46
	v_max3_f32 v225, v225, v61, v62
	s_waitcnt lgkmcnt(4)
	v_mfma_f32_32x32x16_bf16 v[18:33], v[190:193], v[214:217], v[18:33]
	ds_read_b128 v[190:193], v174 offset:32
	v_max3_f32 v224, v224, v47, v48
	v_max3_f32 v225, v225, v63, v64
	v_max3_f32 v224, v224, v49, v65
	v_max_f32_e32 v224, v224, v225
	s_waitcnt lgkmcnt(4)
	v_mfma_f32_32x32x16_bf16 v[2:17], v[194:197], v[218:221], v[2:17]
	ds_read_b128 v[194:197], v174 offset:6688
	v_mov_b32_e32 v225, v224
	v_add_f32_e32 v1, v1, v164
	s_add_i32 s11, s11, 1
	v_permlane32_swap_b32_e32 v224, v225
	s_cmp_eq_u32 s9, s11
	v_max_f32_e32 v167, v224, v225
	v_cmp_lt_f32_e32 vcc, s66, v167
	s_waitcnt lgkmcnt(4)
	v_mfma_f32_32x32x16_bf16 v[18:33], v[198:201], v[218:221], v[18:33]
	s_waitcnt lgkmcnt(7)
	s_barrier

; template <int VAR>
; __device__ __forceinline__ void attn_phase(LAS unsigned char* lds, const AttnP P, int vcu, int G, int wave_s) {
;     ...
;                 if (ND0 == 6) {
;                     KR1(0); KR1(1); KR1(2); KR1(3); SB();
;                     QK1(0, negm); EX2(pc0, 0, w0.x); KR1(4); SB();
;                     QK1(1, negm); EX2(pc0, 2, w0.y); KR1(5); SB();
;                     QK1(2, pn0); EX2(pc0, 4, w0.z); KR1(6); SB();
;                     QK1(3, pn1); EX2(pc0, 6, w0.w); KR1(7); SB();
;                     QK1(4, pn0); EX2(pc0, 8, w1.x); KR1(8); SB();
;                     QK1(5, pn1); EX2(pc0, 10, w1.y); KR1(9); SB();
;                     QK1(6, pn0); EX2(pc0, 12, w1.z); KR1(10); SB();
;                     QK1(7, pn1); EX2(pc0, 14, w1.w); KR1(11); SB();
;                     QK1(8, pn0); EX2(pc1, 0, w2.x); VR1(0); SB();
;                     QK1(9, pn1); EX2(pc1, 2, w2.y); VR1(1); SB();
;                     QK1(10, pn0); EX2(pc1, 4, w2.z); VR1(2); SB();
;                     QK1(11, pn1); EX2(pc1, 6, w2.w); VR1(3); SB();
;                 } else {
;                     KR1(0); KR1(1); KR1(2); KR1(3); SB();
;                     QK1(0, negm); EX2(pc0, 0, w0.x); EX2(pc0, 2, w0.y); KR1(4); SB();
;                     QK1(1, negm); EX2(pc0, 4, w0.z); EX2(pc0, 6, w0.w); KR1(5); SB();
;                     QK1(2, pn0); EX2(pc0, 8, w1.x); EX2(pc0, 10, w1.y); KR1(6); SB();
;                     QK1(3, pn1); EX2(pc0, 12, w1.z); EX2(pc0, 14, w1.w); KR1(7); SB();
;                     QK1(4, pn0); EX2(pc1, 0, w2.x); VR1(0); SB();
;                     QK1(5, pn1); EX2(pc1, 2, w2.y); VR1(1); SB();
;                     QK1(6, pn0); EX2(pc1, 4, w2.z); VR1(2); SB();
;                     QK1(7, pn1); EX2(pc1, 6, w2.w); VR1(3); SB();
;                 }
;                 PV1(0, w0); EX2(pc1, 8, w3.x); VR1(4); SB();
;                 PV1(1, w0); EX2(pc1, 10, w3.y); VR1(5); SB();
;                 PV1(2, w1); EX2(pc1, 12, w3.z); VR1(6); SB();
;                 PV1(3, w1); EX2(pc1, 14, w3.w); VR1(7); SB();
;                 lrun += sacc;
;                 PV1(4, w2); MASK_TILE(pn0, pn1, t + 1); SB();
;                 PV1(5, w2); SB();
;                 PV1(6, w3); SB();
;                 PV1(7, w3); rmn = rowmax32(pn0, pn1); if (!USE_NEGM) rmn -= mref; SB();
;     ...
;             if (hn) { STOREK(t & 1); STOREV((t + 1) & 1); }
;             __syncthreads();
.Lmla_p5_go:
	v_exp_f32_e32 v222, v82
	v_exp_f32_e32 v223, v83
	v_add_f32_e32 v164, 0, v222
	v_cvt_pk_bf16_f32 v206, v222, v223
	v_add_f32_e32 v164, v223, v164
	v_exp_f32_e32 v224, v84
	v_exp_f32_e32 v225, v85
	v_add_f32_e32 v164, v224, v164
	v_cvt_pk_bf16_f32 v207, v224, v225
	v_add_f32_e32 v164, v225, v164
	s_waitcnt lgkmcnt(4)
	v_mfma_f32_32x32x16_bf16 v[34:49], v[182:185], v[114:117], v[66:81]
	ds_read_b128 v[198:201], v174 offset:22592
	v_exp_f32_e32 v222, v86
	v_exp_f32_e32 v223, v87
	v_add_f32_e32 v164, v222, v164
	v_cvt_pk_bf16_f32 v208, v222, v223
	v_add_f32_e32 v164, v223, v164
	s_waitcnt lgkmcnt(4)
	v_mfma_f32_32x32x16_bf16 v[50:65], v[186:189], v[114:117], v[66:81]
	ds_read_b128 v[182:185], v174 offset:29248
	v_exp_f32_e32 v224, v88
	v_exp_f32_e32 v225, v89
	v_add_f32_e32 v164, v224, v164
	v_cvt_pk_bf16_f32 v209, v224, v225
	v_add_f32_e32 v164, v225, v164
	s_waitcnt lgkmcnt(3)
	v_mfma_f32_32x32x16_bf16 v[34:49], v[190:193], v[118:121], v[34:49]
	ds_read_b128 v[186:189], v174 offset:22624
	v_exp_f32_e32 v222, v90
	v_exp_f32_e32 v223, v91
	v_add_f32_e32 v164, v222, v164
	v_cvt_pk_bf16_f32 v210, v222, v223
	v_add_f32_e32 v164, v223, v164
	s_waitcnt lgkmcnt(3)
	v_mfma_f32_32x32x16_bf16 v[50:65], v[194:197], v[118:121], v[50:65]
	ds_read_b128 v[190:193], v174 offset:29280
	v_exp_f32_e32 v224, v92
	v_exp_f32_e32 v225, v93
	v_add_f32_e32 v164, v224, v164
	v_cvt_pk_bf16_f32 v211, v224, v225
	v_add_f32_e32 v164, v225, v164
	s_waitcnt lgkmcnt(3)
	v_mfma_f32_32x32x16_bf16 v[34:49], v[198:201], v[122:125], v[34:49]
	ds_read_b128 v[194:197], v174 offset:22656
	v_exp_f32_e32 v222, v94
	v_exp_f32_e32 v223, v95
	v_add_f32_e32 v164, v222, v164
	v_cvt_pk_bf16_f32 v212, v222, v223
	v_add_f32_e32 v164, v223, v164
	s_waitcnt lgkmcnt(3)
	v_mfma_f32_32x32x16_bf16 v[50:65], v[182:185], v[122:125], v[50:65]
	ds_read_b128 v[198:201], v174 offset:29312
	v_exp_f32_e32 v224, v96
	v_exp_f32_e32 v225, v97
	v_add_f32_e32 v164, v224, v164
	v_cvt_pk_bf16_f32 v213, v224, v225
	v_add_f32_e32 v164, v225, v164
	s_waitcnt lgkmcnt(3)
	v_mfma_f32_32x32x16_bf16 v[34:49], v[186:189], v[126:129], v[34:49]
	ds_read_b128 v[182:185], v174 offset:22688
	v_exp_f32_e32 v222, v98
	v_exp_f32_e32 v223, v99
	v_add_f32_e32 v164, v222, v164
	v_cvt_pk_bf16_f32 v214, v222, v223
	v_add_f32_e32 v164, v223, v164
	s_waitcnt lgkmcnt(3)
	v_mfma_f32_32x32x16_bf16 v[50:65], v[190:193], v[126:129], v[50:65]
	ds_read_b128 v[186:189], v174 offset:29344
	v_exp_f32_e32 v224, v100
	v_exp_f32_e32 v225, v101
	v_add_f32_e32 v164, v224, v164
	v_cvt_pk_bf16_f32 v215, v224, v225
	v_add_f32_e32 v164, v225, v164
	s_waitcnt lgkmcnt(3)
	v_mfma_f32_32x32x16_bf16 v[34:49], v[194:197], v[130:133], v[34:49]
	ds_read_b128 v[190:193], v228 offset:35840
	v_exp_f32_e32 v222, v102
	v_exp_f32_e32 v223, v103
	v_add_f32_e32 v164, v222, v164
	v_cvt_pk_bf16_f32 v216, v222, v223
	v_add_f32_e32 v164, v223, v164
	s_waitcnt lgkmcnt(3)
	v_mfma_f32_32x32x16_bf16 v[50:65], v[198:201], v[130:133], v[50:65]
	ds_read_b128 v[194:197], v228 offset:40448
	v_exp_f32_e32 v224, v104
	v_exp_f32_e32 v225, v105
	v_add_f32_e32 v164, v224, v164
	v_cvt_pk_bf16_f32 v217, v224, v225
	v_add_f32_e32 v164, v225, v164
	s_mov_b32 s13, s20
	s_mov_b32 s20, s19
	s_add_i32 s19, s19, 1
	s_cmp_eq_u32 s19, s9
	s_cselect_b32 s19, 0, s19
	s_waitcnt lgkmcnt(3)
	v_mfma_f32_32x32x16_bf16 v[34:49], v[182:185], v[134:137], v[34:49]
	ds_read_b128 v[198:201], v228 offset:35872
	v_exp_f32_e32 v222, v106
	v_exp_f32_e32 v223, v107
	v_add_f32_e32 v164, v222, v164
	v_cvt_pk_bf16_f32 v218, v222, v223
	v_add_f32_e32 v164, v223, v164
	s_waitcnt vmcnt(2)
	v_add_u32_e32 v222, 0xb000, v172
	ds_write_b128 v222, v[150:153] offset:26624
	v_lshl_add_u32 v222, s19, 17, v178
	global_load_dwordx4 v[150:153], v222, s[52:53]
	s_waitcnt lgkmcnt(4)
	v_mfma_f32_32x32x16_bf16 v[50:65], v[186:189], v[134:137], v[50:65]
	ds_read_b128 v[182:185], v228 offset:40480
	v_exp_f32_e32 v224, v108
	v_exp_f32_e32 v225, v109
	v_add_f32_e32 v164, v224, v164
	v_cvt_pk_bf16_f32 v219, v224, v225
	v_add_f32_e32 v164, v225, v164
	s_and_b64 vcc, exec, s[2:3]
	s_cbranch_vccz .Lmla_p5_nope
	v_add_u32_e32 v222, 0xb000, v176
	ds_write_b128 v222, v[160:163] offset:26752
	v_lshl_add_u32 v222, s19, 12, v179
	global_load_dwordx4 v[160:163], v222, s[62:63]
.Lmla_p5_nope:
	s_waitcnt lgkmcnt(4)
	v_mfma_f32_32x32x16_bf16 v[2:17], v[190:193], v[206:209], v[2:17]
	ds_read_b128 v[186:189], v228 offset:35904
	v_exp_f32_e32 v222, v110
	v_exp_f32_e32 v223, v111
	v_add_f32_e32 v164, v222, v164
	v_cvt_pk_bf16_f32 v220, v222, v223
	v_add_f32_e32 v164, v223, v164
	v_add_u32_e32 v222, 0xb000, v173
	ds_write_b128 v222, v[202:205] offset:49152
	v_lshl_add_u32 v222, s13, 7, v168
	global_load_dwordx4 v[202:205], v222, s[56:57]
	s_waitcnt lgkmcnt(5)
	v_mfma_f32_32x32x16_bf16 v[18:33], v[194:197], v[206:209], v[18:33]
	ds_read_b128 v[190:193], v228 offset:40512
	v_exp_f32_e32 v224, v112
	v_exp_f32_e32 v225, v113
	v_add_f32_e32 v164, v224, v164
	v_cvt_pk_bf16_f32 v221, v224, v225
	v_add_f32_e32 v164, v225, v164
	s_waitcnt lgkmcnt(5)
	v_mfma_f32_32x32x16_bf16 v[2:17], v[198:201], v[210:213], v[2:17]
	ds_read_b128 v[194:197], v228 offset:35936
	v_max3_f32 v224, v34, v35, v36
	v_max3_f32 v225, v50, v51, v52
	v_max3_f32 v224, v224, v37, v38
	v_max3_f32 v225, v225, v53, v54
	s_waitcnt lgkmcnt(4)
	v_mfma_f32_32x32x16_bf16 v[18:33], v[182:185], v[210:213], v[18:33]
	ds_read_b128 v[198:201], v228 offset:40544
	ds_read_b128 v[182:185], v174 offset:45056
	v_max3_f32 v224, v224, v39, v40
	v_max3_f32 v225, v225, v55, v56
	v_max3_f32 v224, v224, v41, v42
	v_max3_f32 v225, v225, v57, v58
	s_waitcnt lgkmcnt(5)
	v_mfma_f32_32x32x16_bf16 v[2:17], v[186:189], v[214:217], v[2:17]
	ds_read_b128 v[186:189], v174 offset:51712
	v_max3_f32 v224, v224, v43, v44
	v_max3_f32 v225, v225, v59, v60
	v_max3_f32 v224, v224, v45, v46
	v_max3_f32 v225, v225, v61, v62
	s_waitcnt lgkmcnt(4)
	v_mfma_f32_32x32x16_bf16 v[18:33], v[190:193], v[214:217], v[18:33]
	ds_read_b128 v[190:193], v174 offset:45088
	v_max3_f32 v224, v224, v47, v48
	v_max3_f32 v225, v225, v63, v64
	v_max3_f32 v224, v224, v49, v65
	v_max_f32_e32 v224, v224, v225
	s_waitcnt lgkmcnt(4)
	v_mfma_f32_32x32x16_bf16 v[2:17], v[194:197], v[218:221], v[2:17]
	ds_read_b128 v[194:197], v174 offset:51744
	v_mov_b32_e32 v225, v224
	v_add_f32_e32 v1, v1, v164
	s_add_i32 s11, s11, 1
	v_permlane32_swap_b32_e32 v224, v225
	s_cmp_eq_u32 s9, s11
	v_max_f32_e32 v167, v224, v225
	v_cmp_lt_f32_e32 vcc, s66, v167
	s_waitcnt lgkmcnt(4)
	v_mfma_f32_32x32x16_bf16 v[18:33], v[198:201], v[218:221], v[18:33]
	s_waitcnt lgkmcnt(7)
	s_barrier

; template <int VAR>
; __device__ __forceinline__ void attn_phase(LAS unsigned char* lds, const AttnP P, int vcu, int G, int wave_s) {
;     ...
;                 if (ND0 == 6) {
;                     KR1(0); KR1(1); KR1(2); KR1(3); SB();
;                     QK1(0, negm); EX2(pc0, 0, w0.x); KR1(4); SB();
;                     QK1(1, negm); EX2(pc0, 2, w0.y); KR1(5); SB();
;                     QK1(2, pn0); EX2(pc0, 4, w0.z); KR1(6); SB();
;                     QK1(3, pn1); EX2(pc0, 6, w0.w); KR1(7); SB();
;                     QK1(4, pn0); EX2(pc0, 8, w1.x); KR1(8); SB();
;                     QK1(5, pn1); EX2(pc0, 10, w1.y); KR1(9); SB();
;                     QK1(6, pn0); EX2(pc0, 12, w1.z); KR1(10); SB();
;                     QK1(7, pn1); EX2(pc0, 14, w1.w); KR1(11); SB();
;                     QK1(8, pn0); EX2(pc1, 0, w2.x); VR1(0); SB();
;                     QK1(9, pn1); EX2(pc1, 2, w2.y); VR1(1); SB();
;                     QK1(10, pn0); EX2(pc1, 4, w2.z); VR1(2); SB();
;                     QK1(11, pn1); EX2(pc1, 6, w2.w); VR1(3); SB();
;                 } else {
;                     KR1(0); KR1(1); KR1(2); KR1(3); SB();
;                     QK1(0, negm); EX2(pc0, 0, w0.x); EX2(pc0, 2, w0.y); KR1(4); SB();
;                     QK1(1, negm); EX2(pc0, 4, w0.z); EX2(pc0, 6, w0.w); KR1(5); SB();
;                     QK1(2, pn0); EX2(pc0, 8, w1.x); EX2(pc0, 10, w1.y); KR1(6); SB();
;                     QK1(3, pn1); EX2(pc0, 12, w1.z); EX2(pc0, 14, w1.w); KR1(7); SB();
;                     QK1(4, pn0); EX2(pc1, 0, w2.x); VR1(0); SB();
;                     QK1(5, pn1); EX2(pc1, 2, w2.y); VR1(1); SB();
;                     QK1(6, pn0); EX2(pc1, 4, w2.z); VR1(2); SB();
;                     QK1(7, pn1); EX2(pc1, 6, w2.w); VR1(3); SB();
;                 }
;                 PV1(0, w0); EX2(pc1, 8, w3.x); VR1(4); SB();
;                 PV1(1, w0); EX2(pc1, 10, w3.y); VR1(5); SB();
;                 PV1(2, w1); EX2(pc1, 12, w3.z); VR1(6); SB();
;                 PV1(3, w1); EX2(pc1, 14, w3.w); VR1(7); SB();
;                 lrun += sacc;
;                 PV1(4, w2); MASK_TILE(pn0, pn1, t + 1); SB();
;                 PV1(5, w2); SB();
;                 PV1(6, w3); SB();
;                 PV1(7, w3); rmn = rowmax32(pn0, pn1); if (!USE_NEGM) rmn -= mref; SB();
;     ...
;             if (hn) { STOREK(t & 1); STOREV((t + 1) & 1); }
;             __syncthreads();
.Lmla_p7_go:
	v_exp_f32_e32 v222, v82
	v_exp_f32_e32 v223, v83
	v_add_f32_e32 v164, 0, v222
	v_cvt_pk_bf16_f32 v206, v222, v223
	v_add_f32_e32 v164, v223, v164
	v_exp_f32_e32 v224, v84
	v_exp_f32_e32 v225, v85
	v_add_f32_e32 v164, v224, v164
	v_cvt_pk_bf16_f32 v207, v224, v225
	v_add_f32_e32 v164, v225, v164
	s_waitcnt lgkmcnt(4)
	v_mfma_f32_32x32x16_bf16 v[34:49], v[182:185], v[114:117], v[66:81]
	ds_read_b128 v[198:201], v229 offset:13376
	v_exp_f32_e32 v222, v86
	v_exp_f32_e32 v223, v87
	v_add_f32_e32 v164, v222, v164
	v_cvt_pk_bf16_f32 v208, v222, v223
	v_add_f32_e32 v164, v223, v164
	s_waitcnt lgkmcnt(4)
	v_mfma_f32_32x32x16_bf16 v[50:65], v[186:189], v[114:117], v[66:81]
	ds_read_b128 v[182:185], v229 offset:20032
	v_exp_f32_e32 v224, v88
	v_exp_f32_e32 v225, v89
	v_add_f32_e32 v164, v224, v164
	v_cvt_pk_bf16_f32 v209, v224, v225
	v_add_f32_e32 v164, v225, v164
	s_waitcnt lgkmcnt(3)
	v_mfma_f32_32x32x16_bf16 v[34:49], v[190:193], v[118:121], v[34:49]
	ds_read_b128 v[186:189], v229 offset:13408
	v_exp_f32_e32 v222, v90
	v_exp_f32_e32 v223, v91
	v_add_f32_e32 v164, v222, v164
	v_cvt_pk_bf16_f32 v210, v222, v223
	v_add_f32_e32 v164, v223, v164
	s_waitcnt lgkmcnt(3)
	v_mfma_f32_32x32x16_bf16 v[50:65], v[194:197], v[118:121], v[50:65]
	ds_read_b128 v[190:193], v229 offset:20064
	v_exp_f32_e32 v224, v92
	v_exp_f32_e32 v225, v93
	v_add_f32_e32 v164, v224, v164
	v_cvt_pk_bf16_f32 v211, v224, v225
	v_add_f32_e32 v164, v225, v164
	s_waitcnt lgkmcnt(3)
	v_mfma_f32_32x32x16_bf16 v[34:49], v[198:201], v[122:125], v[34:49]
	ds_read_b128 v[194:197], v229 offset:13440
	v_exp_f32_e32 v222, v94
	v_exp_f32_e32 v223, v95
	v_add_f32_e32 v164, v222, v164
	v_cvt_pk_bf16_f32 v212, v222, v223
	v_add_f32_e32 v164, v223, v164
	s_waitcnt lgkmcnt(3)
	v_mfma_f32_32x32x16_bf16 v[50:65], v[182:185], v[122:125], v[50:65]
	ds_read_b128 v[198:201], v229 offset:20096
	v_exp_f32_e32 v224, v96
	v_exp_f32_e32 v225, v97
	v_add_f32_e32 v164, v224, v164
	v_cvt_pk_bf16_f32 v213, v224, v225
	v_add_f32_e32 v164, v225, v164
	s_waitcnt lgkmcnt(3)
	v_mfma_f32_32x32x16_bf16 v[34:49], v[186:189], v[126:129], v[34:49]
	ds_read_b128 v[182:185], v229 offset:13472
	v_exp_f32_e32 v222, v98
	v_exp_f32_e32 v223, v99
	v_add_f32_e32 v164, v222, v164
	v_cvt_pk_bf16_f32 v214, v222, v223
	v_add_f32_e32 v164, v223, v164
	s_waitcnt lgkmcnt(3)
	v_mfma_f32_32x32x16_bf16 v[50:65], v[190:193], v[126:129], v[50:65]
	ds_read_b128 v[186:189], v229 offset:20128
	v_exp_f32_e32 v224, v100
	v_exp_f32_e32 v225, v101
	v_add_f32_e32 v164, v224, v164
	v_cvt_pk_bf16_f32 v215, v224, v225
	v_add_f32_e32 v164, v225, v164
	s_waitcnt lgkmcnt(3)
	v_mfma_f32_32x32x16_bf16 v[34:49], v[194:197], v[130:133], v[34:49]
	ds_read_b128 v[190:193], v181 offset:49152
	v_exp_f32_e32 v222, v102
	v_exp_f32_e32 v223, v103
	v_add_f32_e32 v164, v222, v164
	v_cvt_pk_bf16_f32 v216, v222, v223
	v_add_f32_e32 v164, v223, v164
	s_waitcnt lgkmcnt(3)
	v_mfma_f32_32x32x16_bf16 v[50:65], v[198:201], v[130:133], v[50:65]
	ds_read_b128 v[194:197], v181 offset:53760
	v_exp_f32_e32 v224, v104
	v_exp_f32_e32 v225, v105
	v_add_f32_e32 v164, v224, v164
	v_cvt_pk_bf16_f32 v217, v224, v225
	v_add_f32_e32 v164, v225, v164
	s_mov_b32 s13, s20
	s_mov_b32 s20, s19
	s_add_i32 s19, s19, 1
	s_cmp_eq_u32 s19, s9
	s_cselect_b32 s19, 0, s19
	s_waitcnt lgkmcnt(3)
	v_mfma_f32_32x32x16_bf16 v[34:49], v[182:185], v[134:137], v[34:49]
	ds_read_b128 v[198:201], v181 offset:49184
	v_exp_f32_e32 v222, v106
	v_exp_f32_e32 v223, v107
	v_add_f32_e32 v164, v222, v164
	v_cvt_pk_bf16_f32 v218, v222, v223
	v_add_f32_e32 v164, v223, v164
	s_waitcnt vmcnt(2)
	ds_write_b128 v172, v[150:153] offset:22528
	v_lshl_add_u32 v222, s19, 17, v178
	global_load_dwordx4 v[150:153], v222, s[52:53]
	s_waitcnt lgkmcnt(4)
	v_mfma_f32_32x32x16_bf16 v[50:65], v[186:189], v[134:137], v[50:65]
	ds_read_b128 v[182:185], v181 offset:53792
	v_exp_f32_e32 v224, v108
	v_exp_f32_e32 v225, v109
	v_add_f32_e32 v164, v224, v164
	v_cvt_pk_bf16_f32 v219, v224, v225
	v_add_f32_e32 v164, v225, v164
	s_and_b64 vcc, exec, s[2:3]
	s_cbranch_vccz .Lmla_p7_nope
	ds_write_b128 v176, v[160:163] offset:22656
	v_lshl_add_u32 v222, s19, 12, v179
	global_load_dwordx4 v[160:163], v222, s[62:63]
.Lmla_p7_nope:
	s_waitcnt lgkmcnt(4)
	v_mfma_f32_32x32x16_bf16 v[2:17], v[190:193], v[206:209], v[2:17]
	ds_read_b128 v[186:189], v181 offset:49216
	v_exp_f32_e32 v222, v110
	v_exp_f32_e32 v223, v111
	v_add_f32_e32 v164, v222, v164
	v_cvt_pk_bf16_f32 v220, v222, v223
	v_add_f32_e32 v164, v223, v164
	ds_write_b128 v173, v[202:205] offset:35840
	v_lshl_add_u32 v222, s13, 7, v168
	global_load_dwordx4 v[202:205], v222, s[56:57]
	s_waitcnt lgkmcnt(5)
	v_mfma_f32_32x32x16_bf16 v[18:33], v[194:197], v[206:209], v[18:33]
	ds_read_b128 v[190:193], v181 offset:53824
	v_exp_f32_e32 v224, v112
	v_exp_f32_e32 v225, v113
	v_add_f32_e32 v164, v224, v164
	v_cvt_pk_bf16_f32 v221, v224, v225
	v_add_f32_e32 v164, v225, v164
	s_waitcnt lgkmcnt(5)
	v_mfma_f32_32x32x16_bf16 v[2:17], v[198:201], v[210:213], v[2:17]
	ds_read_b128 v[194:197], v181 offset:49248
	v_max3_f32 v224, v34, v35, v36
	v_max3_f32 v225, v50, v51, v52
	v_max3_f32 v224, v224, v37, v38
	v_max3_f32 v225, v225, v53, v54
	s_waitcnt lgkmcnt(4)
	v_mfma_f32_32x32x16_bf16 v[18:33], v[182:185], v[210:213], v[18:33]
	ds_read_b128 v[198:201], v181 offset:53856
	ds_read_b128 v[182:185], v229 offset:26624
	v_max3_f32 v224, v224, v39, v40
	v_max3_f32 v225, v225, v55, v56
	v_max3_f32 v224, v224, v41, v42
	v_max3_f32 v225, v225, v57, v58
	s_waitcnt lgkmcnt(5)
	v_mfma_f32_32x32x16_bf16 v[2:17], v[186:189], v[214:217], v[2:17]
	ds_read_b128 v[186:189], v229 offset:33280
	v_max3_f32 v224, v224, v43, v44
	v_max3_f32 v225, v225, v59, v60
	v_max3_f32 v224, v224, v45, v46
	v_max3_f32 v225, v225, v61, v62
	s_waitcnt lgkmcnt(4)
	v_mfma_f32_32x32x16_bf16 v[18:33], v[190:193], v[214:217], v[18:33]
	ds_read_b128 v[190:193], v229 offset:26656
	v_max3_f32 v224, v224, v47, v48
	v_max3_f32 v225, v225, v63, v64
	v_max3_f32 v224, v224, v49, v65
	v_max_f32_e32 v224, v224, v225
	s_waitcnt lgkmcnt(4)
	v_mfma_f32_32x32x16_bf16 v[2:17], v[194:197], v[218:221], v[2:17]
	ds_read_b128 v[194:197], v229 offset:33312
	v_mov_b32_e32 v225, v224
	v_add_f32_e32 v1, v1, v164
	s_add_i32 s11, s11, 1
	v_permlane32_swap_b32_e32 v224, v225
	s_cmp_eq_u32 s9, s11
	v_max_f32_e32 v167, v224, v225
	v_cmp_lt_f32_e32 vcc, s66, v167
	s_waitcnt lgkmcnt(4)
	v_mfma_f32_32x32x16_bf16 v[18:33], v[198:201], v[218:221], v[18:33]
	s_waitcnt lgkmcnt(7)
	s_barrier

; template <int VAR>
; __device__ __forceinline__ void attn_phase(LAS unsigned char* lds, const AttnP P, int vcu, int G, int wave_s) {
;     ...
;                 if (ND0 == 6) {
;                     KR1(0); KR1(1); KR1(2); KR1(3); SB();
;                     QK1(0, negm); EX2(pc0, 0, w0.x); KR1(4); SB();
;                     QK1(1, negm); EX2(pc0, 2, w0.y); KR1(5); SB();
;                     QK1(2, pn0); EX2(pc0, 4, w0.z); KR1(6); SB();
;                     QK1(3, pn1); EX2(pc0, 6, w0.w); KR1(7); SB();
;                     QK1(4, pn0); EX2(pc0, 8, w1.x); KR1(8); SB();
;                     QK1(5, pn1); EX2(pc0, 10, w1.y); KR1(9); SB();
;                     QK1(6, pn0); EX2(pc0, 12, w1.z); KR1(10); SB();
;                     QK1(7, pn1); EX2(pc0, 14, w1.w); KR1(11); SB();
;                     QK1(8, pn0); EX2(pc1, 0, w2.x); VR1(0); SB();
;                     QK1(9, pn1); EX2(pc1, 2, w2.y); VR1(1); SB();
;                     QK1(10, pn0); EX2(pc1, 4, w2.z); VR1(2); SB();
;                     QK1(11, pn1); EX2(pc1, 6, w2.w); VR1(3); SB();
;                 } else {
;                     KR1(0); KR1(1); KR1(2); KR1(3); SB();
;                     QK1(0, negm); EX2(pc0, 0, w0.x); EX2(pc0, 2, w0.y); KR1(4); SB();
;                     QK1(1, negm); EX2(pc0, 4, w0.z); EX2(pc0, 6, w0.w); KR1(5); SB();
;                     QK1(2, pn0); EX2(pc0, 8, w1.x); EX2(pc0, 10, w1.y); KR1(6); SB();
;                     QK1(3, pn1); EX2(pc0, 12, w1.z); EX2(pc0, 14, w1.w); KR1(7); SB();
;                     QK1(4, pn0); EX2(pc1, 0, w2.x); VR1(0); SB();
;                     QK1(5, pn1); EX2(pc1, 2, w2.y); VR1(1); SB();
;                     QK1(6, pn0); EX2(pc1, 4, w2.z); VR1(2); SB();
;                     QK1(7, pn1); EX2(pc1, 6, w2.w); VR1(3); SB();
;                 }
;                 PV1(0, w0); EX2(pc1, 8, w3.x); VR1(4); SB();
;                 PV1(1, w0); EX2(pc1, 10, w3.y); VR1(5); SB();
;                 PV1(2, w1); EX2(pc1, 12, w3.z); VR1(6); SB();
;                 PV1(3, w1); EX2(pc1, 14, w3.w); VR1(7); SB();
;                 lrun += sacc;
;                 PV1(4, w2); MASK_TILE(pn0, pn1, t + 1); SB();
;                 PV1(5, w2); SB();
;                 PV1(6, w3); SB();
;                 PV1(7, w3); rmn = rowmax32(pn0, pn1); if (!USE_NEGM) rmn -= mref; SB();
;     ...
;             if (hn) { STOREK(t & 1); STOREV((t + 1) & 1); }
;             __syncthreads();
.Lmla_p9_go:
	v_exp_f32_e32 v222, v82
	v_exp_f32_e32 v223, v83
	v_add_f32_e32 v164, 0, v222
	v_cvt_pk_bf16_f32 v206, v222, v223
	v_add_f32_e32 v164, v223, v164
	v_exp_f32_e32 v224, v84
	v_exp_f32_e32 v225, v85
	v_add_f32_e32 v164, v224, v164
	v_cvt_pk_bf16_f32 v207, v224, v225
	v_add_f32_e32 v164, v225, v164
	s_waitcnt lgkmcnt(4)
	v_mfma_f32_32x32x16_bf16 v[34:49], v[182:185], v[114:117], v[66:81]
	ds_read_b128 v[198:201], v174 offset:64
	v_exp_f32_e32 v222, v86
	v_exp_f32_e32 v223, v87
	v_add_f32_e32 v164, v222, v164
	v_cvt_pk_bf16_f32 v208, v222, v223
	v_add_f32_e32 v164, v223, v164
	s_waitcnt lgkmcnt(4)
	v_mfma_f32_32x32x16_bf16 v[50:65], v[186:189], v[114:117], v[66:81]
	ds_read_b128 v[182:185], v174 offset:6720
	v_exp_f32_e32 v224, v88
	v_exp_f32_e32 v225, v89
	v_add_f32_e32 v164, v224, v164
	v_cvt_pk_bf16_f32 v209, v224, v225
	v_add_f32_e32 v164, v225, v164
	s_waitcnt lgkmcnt(3)
	v_mfma_f32_32x32x16_bf16 v[34:49], v[190:193], v[118:121], v[34:49]
	ds_read_b128 v[186:189], v174 offset:96
	v_exp_f32_e32 v222, v90
	v_exp_f32_e32 v223, v91
	v_add_f32_e32 v164, v222, v164
	v_cvt_pk_bf16_f32 v210, v222, v223
	v_add_f32_e32 v164, v223, v164
	s_waitcnt lgkmcnt(3)
	v_mfma_f32_32x32x16_bf16 v[50:65], v[194:197], v[118:121], v[50:65]
	ds_read_b128 v[190:193], v174 offset:6752
	v_exp_f32_e32 v224, v92
	v_exp_f32_e32 v225, v93
	v_add_f32_e32 v164, v224, v164
	v_cvt_pk_bf16_f32 v211, v224, v225
	v_add_f32_e32 v164, v225, v164
	s_waitcnt lgkmcnt(3)
	v_mfma_f32_32x32x16_bf16 v[34:49], v[198:201], v[122:125], v[34:49]
	ds_read_b128 v[194:197], v174 offset:128
	v_exp_f32_e32 v222, v94
	v_exp_f32_e32 v223, v95
	v_add_f32_e32 v164, v222, v164
	v_cvt_pk_bf16_f32 v212, v222, v223
	v_add_f32_e32 v164, v223, v164
	s_waitcnt lgkmcnt(3)
	v_mfma_f32_32x32x16_bf16 v[50:65], v[182:185], v[122:125], v[50:65]
	ds_read_b128 v[198:201], v174 offset:6784
	v_exp_f32_e32 v224, v96
	v_exp_f32_e32 v225, v97
	v_add_f32_e32 v164, v224, v164
	v_cvt_pk_bf16_f32 v213, v224, v225
	v_add_f32_e32 v164, v225, v164
	s_waitcnt lgkmcnt(3)
	v_mfma_f32_32x32x16_bf16 v[34:49], v[186:189], v[126:129], v[34:49]
	ds_read_b128 v[182:185], v174 offset:160
	v_exp_f32_e32 v222, v98
	v_exp_f32_e32 v223, v99
	v_add_f32_e32 v164, v222, v164
	v_cvt_pk_bf16_f32 v214, v222, v223
	v_add_f32_e32 v164, v223, v164
	s_waitcnt lgkmcnt(3)
	v_mfma_f32_32x32x16_bf16 v[50:65], v[190:193], v[126:129], v[50:65]
	ds_read_b128 v[186:189], v174 offset:6816
	v_exp_f32_e32 v224, v100
	v_exp_f32_e32 v225, v101
	v_add_f32_e32 v164, v224, v164
	v_cvt_pk_bf16_f32 v215, v224, v225
	v_add_f32_e32 v164, v225, v164
	s_waitcnt lgkmcnt(3)
	v_mfma_f32_32x32x16_bf16 v[34:49], v[194:197], v[130:133], v[34:49]
	ds_read_b128 v[190:193], v228 offset:35840
	v_exp_f32_e32 v222, v102
	v_exp_f32_e32 v223, v103
	v_add_f32_e32 v164, v222, v164
	v_cvt_pk_bf16_f32 v216, v222, v223
	v_add_f32_e32 v164, v223, v164
	s_waitcnt lgkmcnt(3)
	v_mfma_f32_32x32x16_bf16 v[50:65], v[198:201], v[130:133], v[50:65]
	ds_read_b128 v[194:197], v228 offset:40448
	v_exp_f32_e32 v224, v104
	v_exp_f32_e32 v225, v105
	v_add_f32_e32 v164, v224, v164
	v_cvt_pk_bf16_f32 v217, v224, v225
	v_add_f32_e32 v164, v225, v164
	s_mov_b32 s13, s20
	s_mov_b32 s20, s19
	s_add_i32 s19, s19, 1
	s_cmp_eq_u32 s19, s9
	s_cselect_b32 s19, 0, s19
	s_waitcnt lgkmcnt(3)
	v_mfma_f32_32x32x16_bf16 v[34:49], v[182:185], v[134:137], v[34:49]
	ds_read_b128 v[198:201], v228 offset:35872
	v_exp_f32_e32 v222, v106
	v_exp_f32_e32 v223, v107
	v_add_f32_e32 v164, v222, v164
	v_cvt_pk_bf16_f32 v218, v222, v223
	v_add_f32_e32 v164, v223, v164
	s_waitcnt vmcnt(2)
	ds_write_b128 v172, v[150:153] offset:58368
	v_lshl_add_u32 v222, s19, 17, v178
	global_load_dwordx4 v[150:153], v222, s[52:53]
	s_waitcnt lgkmcnt(4)
	v_mfma_f32_32x32x16_bf16 v[50:65], v[186:189], v[134:137], v[50:65]
	ds_read_b128 v[182:185], v228 offset:40480
	v_exp_f32_e32 v224, v108
	v_exp_f32_e32 v225, v109
	v_add_f32_e32 v164, v224, v164
	v_cvt_pk_bf16_f32 v219, v224, v225
	v_add_f32_e32 v164, v225, v164
	s_and_b64 vcc, exec, s[2:3]
	s_cbranch_vccz .Lmla_p9_nope
	ds_write_b128 v176, v[160:163] offset:58496
	v_lshl_add_u32 v222, s19, 12, v179
	global_load_dwordx4 v[160:163], v222, s[62:63]
.Lmla_p9_nope:
	s_waitcnt lgkmcnt(4)
	v_mfma_f32_32x32x16_bf16 v[2:17], v[190:193], v[206:209], v[2:17]
	ds_read_b128 v[186:189], v228 offset:35904
	v_exp_f32_e32 v222, v110
	v_exp_f32_e32 v223, v111
	v_add_f32_e32 v164, v222, v164
	v_cvt_pk_bf16_f32 v220, v222, v223
	v_add_f32_e32 v164, v223, v164
	v_add_u32_e32 v222, 0xb000, v173
	ds_write_b128 v222, v[202:205] offset:49152
	v_lshl_add_u32 v222, s13, 7, v168
	global_load_dwordx4 v[202:205], v222, s[56:57]
	s_waitcnt lgkmcnt(5)
	v_mfma_f32_32x32x16_bf16 v[18:33], v[194:197], v[206:209], v[18:33]
	ds_read_b128 v[190:193], v228 offset:40512
	v_exp_f32_e32 v224, v112
	v_exp_f32_e32 v225, v113
	v_add_f32_e32 v164, v224, v164
	v_cvt_pk_bf16_f32 v221, v224, v225
	v_add_f32_e32 v164, v225, v164
	s_waitcnt lgkmcnt(5)
	v_mfma_f32_32x32x16_bf16 v[2:17], v[198:201], v[210:213], v[2:17]
	ds_read_b128 v[194:197], v228 offset:35936
	v_max3_f32 v224, v34, v35, v36
	v_max3_f32 v225, v50, v51, v52
	v_max3_f32 v224, v224, v37, v38
	v_max3_f32 v225, v225, v53, v54
	s_waitcnt lgkmcnt(4)
	v_mfma_f32_32x32x16_bf16 v[18:33], v[182:185], v[210:213], v[18:33]
	ds_read_b128 v[198:201], v228 offset:40544
	ds_read_b128 v[182:185], v174 offset:22528
	v_max3_f32 v224, v224, v39, v40
	v_max3_f32 v225, v225, v55, v56
	v_max3_f32 v224, v224, v41, v42
	v_max3_f32 v225, v225, v57, v58
	s_waitcnt lgkmcnt(5)
	v_mfma_f32_32x32x16_bf16 v[2:17], v[186:189], v[214:217], v[2:17]
	ds_read_b128 v[186:189], v174 offset:29184
	v_max3_f32 v224, v224, v43, v44
	v_max3_f32 v225, v225, v59, v60
	v_max3_f32 v224, v224, v45, v46
	v_max3_f32 v225, v225, v61, v62
	s_waitcnt lgkmcnt(4)
	v_mfma_f32_32x32x16_bf16 v[18:33], v[190:193], v[214:217], v[18:33]
	ds_read_b128 v[190:193], v174 offset:22560
	v_max3_f32 v224, v224, v47, v48
	v_max3_f32 v225, v225, v63, v64
	v_max3_f32 v224, v224, v49, v65
	v_max_f32_e32 v224, v224, v225
	s_waitcnt lgkmcnt(4)
	v_mfma_f32_32x32x16_bf16 v[2:17], v[194:197], v[218:221], v[2:17]
	ds_read_b128 v[194:197], v174 offset:29216
	v_mov_b32_e32 v225, v224
	v_add_f32_e32 v1, v1, v164
	s_add_i32 s11, s11, 1
	v_permlane32_swap_b32_e32 v224, v225
	s_cmp_eq_u32 s9, s11
	v_max_f32_e32 v167, v224, v225
	v_cmp_lt_f32_e32 vcc, s66, v167
	s_waitcnt lgkmcnt(4)
	v_mfma_f32_32x32x16_bf16 v[18:33], v[198:201], v[218:221], v[18:33]
	s_waitcnt lgkmcnt(7)
	s_barrier

; template <int VAR>
; __device__ __forceinline__ void attn_phase(LAS unsigned char* lds, const AttnP P, int vcu, int G, int wave_s) {
;     ...
;                 if (ND0 == 6) {
;                     KR1(0); KR1(1); KR1(2); KR1(3); SB();
;                     QK1(0, negm); EX2(pc0, 0, w0.x); KR1(4); SB();
;                     QK1(1, negm); EX2(pc0, 2, w0.y); KR1(5); SB();
;                     QK1(2, pn0); EX2(pc0, 4, w0.z); KR1(6); SB();
;                     QK1(3, pn1); EX2(pc0, 6, w0.w); KR1(7); SB();
;                     QK1(4, pn0); EX2(pc0, 8, w1.x); KR1(8); SB();
;                     QK1(5, pn1); EX2(pc0, 10, w1.y); KR1(9); SB();
;                     QK1(6, pn0); EX2(pc0, 12, w1.z); KR1(10); SB();
;                     QK1(7, pn1); EX2(pc0, 14, w1.w); KR1(11); SB();
;                     QK1(8, pn0); EX2(pc1, 0, w2.x); VR1(0); SB();
;                     QK1(9, pn1); EX2(pc1, 2, w2.y); VR1(1); SB();
;                     QK1(10, pn0); EX2(pc1, 4, w2.z); VR1(2); SB();
;                     QK1(11, pn1); EX2(pc1, 6, w2.w); VR1(3); SB();
;                 } else {
;                     KR1(0); KR1(1); KR1(2); KR1(3); SB();
;                     QK1(0, negm); EX2(pc0, 0, w0.x); EX2(pc0, 2, w0.y); KR1(4); SB();
;                     QK1(1, negm); EX2(pc0, 4, w0.z); EX2(pc0, 6, w0.w); KR1(5); SB();
;                     QK1(2, pn0); EX2(pc0, 8, w1.x); EX2(pc0, 10, w1.y); KR1(6); SB();
;                     QK1(3, pn1); EX2(pc0, 12, w1.z); EX2(pc0, 14, w1.w); KR1(7); SB();
;                     QK1(4, pn0); EX2(pc1, 0, w2.x); VR1(0); SB();
;                     QK1(5, pn1); EX2(pc1, 2, w2.y); VR1(1); SB();
;                     QK1(6, pn0); EX2(pc1, 4, w2.z); VR1(2); SB();
;                     QK1(7, pn1); EX2(pc1, 6, w2.w); VR1(3); SB();
;                 }
;                 PV1(0, w0); EX2(pc1, 8, w3.x); VR1(4); SB();
;                 PV1(1, w0); EX2(pc1, 10, w3.y); VR1(5); SB();
;                 PV1(2, w1); EX2(pc1, 12, w3.z); VR1(6); SB();
;                 PV1(3, w1); EX2(pc1, 14, w3.w); VR1(7); SB();
;                 lrun += sacc;
;                 PV1(4, w2); MASK_TILE(pn0, pn1, t + 1); SB();
;                 PV1(5, w2); SB();
;                 PV1(6, w3); SB();
;                 PV1(7, w3); rmn = rowmax32(pn0, pn1); if (!USE_NEGM) rmn -= mref; SB();
;     ...
;             if (hn) { STOREK(t & 1); STOREV((t + 1) & 1); }
;             __syncthreads();
.Lmla_p11_go:
	v_exp_f32_e32 v222, v82
	v_exp_f32_e32 v223, v83
	v_add_f32_e32 v164, 0, v222
	v_cvt_pk_bf16_f32 v206, v222, v223
	v_add_f32_e32 v164, v223, v164
	v_exp_f32_e32 v224, v84
	v_exp_f32_e32 v225, v85
	v_add_f32_e32 v164, v224, v164
	v_cvt_pk_bf16_f32 v207, v224, v225
	v_add_f32_e32 v164, v225, v164
	s_waitcnt lgkmcnt(4)
	v_mfma_f32_32x32x16_bf16 v[34:49], v[182:185], v[114:117], v[66:81]
	ds_read_b128 v[198:201], v174 offset:45120
	v_exp_f32_e32 v222, v86
	v_exp_f32_e32 v223, v87
	v_add_f32_e32 v164, v222, v164
	v_cvt_pk_bf16_f32 v208, v222, v223
	v_add_f32_e32 v164, v223, v164
	s_waitcnt lgkmcnt(4)
	v_mfma_f32_32x32x16_bf16 v[50:65], v[186:189], v[114:117], v[66:81]
	ds_read_b128 v[182:185], v174 offset:51776
	v_exp_f32_e32 v224, v88
	v_exp_f32_e32 v225, v89
	v_add_f32_e32 v164, v224, v164
	v_cvt_pk_bf16_f32 v209, v224, v225
	v_add_f32_e32 v164, v225, v164
	s_waitcnt lgkmcnt(3)
	v_mfma_f32_32x32x16_bf16 v[34:49], v[190:193], v[118:121], v[34:49]
	ds_read_b128 v[186:189], v174 offset:45152
	v_exp_f32_e32 v222, v90
	v_exp_f32_e32 v223, v91
	v_add_f32_e32 v164, v222, v164
	v_cvt_pk_bf16_f32 v210, v222, v223
	v_add_f32_e32 v164, v223, v164
	s_waitcnt lgkmcnt(3)
	v_mfma_f32_32x32x16_bf16 v[50:65], v[194:197], v[118:121], v[50:65]
	ds_read_b128 v[190:193], v174 offset:51808
	v_exp_f32_e32 v224, v92
	v_exp_f32_e32 v225, v93
	v_add_f32_e32 v164, v224, v164
	v_cvt_pk_bf16_f32 v211, v224, v225
	v_add_f32_e32 v164, v225, v164
	s_waitcnt lgkmcnt(3)
	v_mfma_f32_32x32x16_bf16 v[34:49], v[198:201], v[122:125], v[34:49]
	ds_read_b128 v[194:197], v174 offset:45184
	v_exp_f32_e32 v222, v94
	v_exp_f32_e32 v223, v95
	v_add_f32_e32 v164, v222, v164
	v_cvt_pk_bf16_f32 v212, v222, v223
	v_add_f32_e32 v164, v223, v164
	s_waitcnt lgkmcnt(3)
	v_mfma_f32_32x32x16_bf16 v[50:65], v[182:185], v[122:125], v[50:65]
	ds_read_b128 v[198:201], v174 offset:51840
	v_exp_f32_e32 v224, v96
	v_exp_f32_e32 v225, v97
	v_add_f32_e32 v164, v224, v164
	v_cvt_pk_bf16_f32 v213, v224, v225
	v_add_f32_e32 v164, v225, v164
	s_waitcnt lgkmcnt(3)
	v_mfma_f32_32x32x16_bf16 v[34:49], v[186:189], v[126:129], v[34:49]
	ds_read_b128 v[182:185], v174 offset:45216
	v_exp_f32_e32 v222, v98
	v_exp_f32_e32 v223, v99
	v_add_f32_e32 v164, v222, v164
	v_cvt_pk_bf16_f32 v214, v222, v223
	v_add_f32_e32 v164, v223, v164
	s_waitcnt lgkmcnt(3)
	v_mfma_f32_32x32x16_bf16 v[50:65], v[190:193], v[126:129], v[50:65]
	ds_read_b128 v[186:189], v174 offset:51872
	v_exp_f32_e32 v224, v100
	v_exp_f32_e32 v225, v101
	v_add_f32_e32 v164, v224, v164
	v_cvt_pk_bf16_f32 v215, v224, v225
	v_add_f32_e32 v164, v225, v164
	s_waitcnt lgkmcnt(3)
	v_mfma_f32_32x32x16_bf16 v[34:49], v[194:197], v[130:133], v[34:49]
	ds_read_b128 v[190:193], v181 offset:49152
	v_exp_f32_e32 v222, v102
	v_exp_f32_e32 v223, v103
	v_add_f32_e32 v164, v222, v164
	v_cvt_pk_bf16_f32 v216, v222, v223
	v_add_f32_e32 v164, v223, v164
	s_waitcnt lgkmcnt(3)
	v_mfma_f32_32x32x16_bf16 v[50:65], v[198:201], v[130:133], v[50:65]
	ds_read_b128 v[194:197], v181 offset:53760
	v_exp_f32_e32 v224, v104
	v_exp_f32_e32 v225, v105
	v_add_f32_e32 v164, v224, v164
	v_cvt_pk_bf16_f32 v217, v224, v225
	v_add_f32_e32 v164, v225, v164
	s_mov_b32 s13, s20
	s_mov_b32 s20, s19
	s_add_i32 s19, s19, 1
	s_cmp_eq_u32 s19, s9
	s_cselect_b32 s19, 0, s19
	s_waitcnt lgkmcnt(3)
	v_mfma_f32_32x32x16_bf16 v[34:49], v[182:185], v[134:137], v[34:49]
	ds_read_b128 v[198:201], v181 offset:49184
	v_exp_f32_e32 v222, v106
	v_exp_f32_e32 v223, v107
	v_add_f32_e32 v164, v222, v164
	v_cvt_pk_bf16_f32 v218, v222, v223
	v_add_f32_e32 v164, v223, v164
	s_waitcnt vmcnt(2)
	ds_write_b128 v172, v[150:153]
	v_lshl_add_u32 v222, s19, 17, v178
	global_load_dwordx4 v[150:153], v222, s[52:53]
	s_waitcnt lgkmcnt(4)
	v_mfma_f32_32x32x16_bf16 v[50:65], v[186:189], v[134:137], v[50:65]
	ds_read_b128 v[182:185], v181 offset:53792
	v_exp_f32_e32 v224, v108
	v_exp_f32_e32 v225, v109
	v_add_f32_e32 v164, v224, v164
	v_cvt_pk_bf16_f32 v219, v224, v225
	v_add_f32_e32 v164, v225, v164
	s_and_b64 vcc, exec, s[2:3]
	s_cbranch_vccz .Lmla_p11_nope
	ds_write_b128 v176, v[160:163] offset:128
	v_lshl_add_u32 v222, s19, 12, v179
	global_load_dwordx4 v[160:163], v222, s[62:63]
.Lmla_p11_nope:
	s_waitcnt lgkmcnt(4)
	v_mfma_f32_32x32x16_bf16 v[2:17], v[190:193], v[206:209], v[2:17]
	ds_read_b128 v[186:189], v181 offset:49216
	v_exp_f32_e32 v222, v110
	v_exp_f32_e32 v223, v111
	v_add_f32_e32 v164, v222, v164
	v_cvt_pk_bf16_f32 v220, v222, v223
	v_add_f32_e32 v164, v223, v164
	ds_write_b128 v173, v[202:205] offset:35840
	v_lshl_add_u32 v222, s13, 7, v168
	global_load_dwordx4 v[202:205], v222, s[56:57]
	s_waitcnt lgkmcnt(5)
	v_mfma_f32_32x32x16_bf16 v[18:33], v[194:197], v[206:209], v[18:33]
	ds_read_b128 v[190:193], v181 offset:53824
	v_exp_f32_e32 v224, v112
	v_exp_f32_e32 v225, v113
	v_add_f32_e32 v164, v224, v164
	v_cvt_pk_bf16_f32 v221, v224, v225
	v_add_f32_e32 v164, v225, v164
	s_waitcnt lgkmcnt(5)
	v_mfma_f32_32x32x16_bf16 v[2:17], v[198:201], v[210:213], v[2:17]
	ds_read_b128 v[194:197], v181 offset:49248
	v_max3_f32 v224, v34, v35, v36
	v_max3_f32 v225, v50, v51, v52
	v_max3_f32 v224, v224, v37, v38
	v_max3_f32 v225, v225, v53, v54
	s_waitcnt lgkmcnt(4)
	v_mfma_f32_32x32x16_bf16 v[18:33], v[182:185], v[210:213], v[18:33]
	ds_read_b128 v[198:201], v181 offset:53856
	ds_read_b128 v[182:185], v229 offset:13312
	v_max3_f32 v224, v224, v39, v40
	v_max3_f32 v225, v225, v55, v56
	v_max3_f32 v224, v224, v41, v42
	v_max3_f32 v225, v225, v57, v58
	s_waitcnt lgkmcnt(5)
	v_mfma_f32_32x32x16_bf16 v[2:17], v[186:189], v[214:217], v[2:17]
	ds_read_b128 v[186:189], v229 offset:19968
	v_max3_f32 v224, v224, v43, v44
	v_max3_f32 v225, v225, v59, v60
	v_max3_f32 v224, v224, v45, v46
	v_max3_f32 v225, v225, v61, v62
	s_waitcnt lgkmcnt(4)
	v_mfma_f32_32x32x16_bf16 v[18:33], v[190:193], v[214:217], v[18:33]
	ds_read_b128 v[190:193], v229 offset:13344
	v_max3_f32 v224, v224, v47, v48
	v_max3_f32 v225, v225, v63, v64
	v_max3_f32 v224, v224, v49, v65
	v_max_f32_e32 v224, v224, v225
	s_waitcnt lgkmcnt(4)
	v_mfma_f32_32x32x16_bf16 v[2:17], v[194:197], v[218:221], v[2:17]
	ds_read_b128 v[194:197], v229 offset:20000
	v_mov_b32_e32 v225, v224
	v_add_f32_e32 v1, v1, v164
	s_add_i32 s11, s11, 1
	v_permlane32_swap_b32_e32 v224, v225
	s_cmp_eq_u32 s9, s11
	v_max_f32_e32 v167, v224, v225
	v_cmp_lt_f32_e32 vcc, s66, v167
	s_waitcnt lgkmcnt(4)
	v_mfma_f32_32x32x16_bf16 v[18:33], v[198:201], v[218:221], v[18:33]
	s_waitcnt lgkmcnt(7)
	s_barrier

; template <int VAR>
; __device__ __forceinline__ void attn_phase(LAS unsigned char* lds, const AttnP P, int vcu, int G, int wave_s) {
;     ...
;                 if (ND0 == 6) {
;                     KR1(0); KR1(1); KR1(2); KR1(3); SB();
;                     QK1(0, negm); EX2(pc0, 0, w0.x); KR1(4); SB();
;                     QK1(1, negm); EX2(pc0, 2, w0.y); KR1(5); SB();
;                     QK1(2, pn0); EX2(pc0, 4, w0.z); KR1(6); SB();
;                     QK1(3, pn1); EX2(pc0, 6, w0.w); KR1(7); SB();
;                     QK1(4, pn0); EX2(pc0, 8, w1.x); KR1(8); SB();
;                     QK1(5, pn1); EX2(pc0, 10, w1.y); KR1(9); SB();
;                     QK1(6, pn0); EX2(pc0, 12, w1.z); KR1(10); SB();
;                     QK1(7, pn1); EX2(pc0, 14, w1.w); KR1(11); SB();
;                     QK1(8, pn0); EX2(pc1, 0, w2.x); VR1(0); SB();
;                     QK1(9, pn1); EX2(pc1, 2, w2.y); VR1(1); SB();
;                     QK1(10, pn0); EX2(pc1, 4, w2.z); VR1(2); SB();
;                     QK1(11, pn1); EX2(pc1, 6, w2.w); VR1(3); SB();
;                 } else {
;                     KR1(0); KR1(1); KR1(2); KR1(3); SB();
;                     QK1(0, negm); EX2(pc0, 0, w0.x); EX2(pc0, 2, w0.y); KR1(4); SB();
;                     QK1(1, negm); EX2(pc0, 4, w0.z); EX2(pc0, 6, w0.w); KR1(5); SB();
;                     QK1(2, pn0); EX2(pc0, 8, w1.x); EX2(pc0, 10, w1.y); KR1(6); SB();
;                     QK1(3, pn1); EX2(pc0, 12, w1.z); EX2(pc0, 14, w1.w); KR1(7); SB();
;                     QK1(4, pn0); EX2(pc1, 0, w2.x); VR1(0); SB();
;                     QK1(5, pn1); EX2(pc1, 2, w2.y); VR1(1); SB();
;                     QK1(6, pn0); EX2(pc1, 4, w2.z); VR1(2); SB();
;                     QK1(7, pn1); EX2(pc1, 6, w2.w); VR1(3); SB();
;                 }
;                 PV1(0, w0); EX2(pc1, 8, w3.x); VR1(4); SB();
;                 PV1(1, w0); EX2(pc1, 10, w3.y); VR1(5); SB();
;                 PV1(2, w1); EX2(pc1, 12, w3.z); VR1(6); SB();
;                 PV1(3, w1); EX2(pc1, 14, w3.w); VR1(7); SB();
;                 lrun += sacc;
;                 PV1(4, w2); MASK_TILE(pn0, pn1, t + 1); SB();
;                 PV1(5, w2); SB();
;                 PV1(6, w3); SB();
;                 PV1(7, w3); rmn = rowmax32(pn0, pn1); if (!USE_NEGM) rmn -= mref; SB();
;     ...
;             if (hn) { STOREK(t & 1); STOREV((t + 1) & 1); }
;             __syncthreads();
.Lmla_p13_go:
	v_exp_f32_e32 v222, v82
	v_exp_f32_e32 v223, v83
	v_add_f32_e32 v164, 0, v222
	v_cvt_pk_bf16_f32 v206, v222, v223
	v_add_f32_e32 v164, v223, v164
	v_exp_f32_e32 v224, v84
	v_exp_f32_e32 v225, v85
	v_add_f32_e32 v164, v224, v164
	v_cvt_pk_bf16_f32 v207, v224, v225
	v_add_f32_e32 v164, v225, v164
	s_waitcnt lgkmcnt(4)
	v_mfma_f32_32x32x16_bf16 v[34:49], v[182:185], v[114:117], v[66:81]
	ds_read_b128 v[198:201], v229 offset:26688
	v_exp_f32_e32 v222, v86
	v_exp_f32_e32 v223, v87
	v_add_f32_e32 v164, v222, v164
	v_cvt_pk_bf16_f32 v208, v222, v223
	v_add_f32_e32 v164, v223, v164
	s_waitcnt lgkmcnt(4)
	v_mfma_f32_32x32x16_bf16 v[50:65], v[186:189], v[114:117], v[66:81]
	ds_read_b128 v[182:185], v229 offset:33344
	v_exp_f32_e32 v224, v88
	v_exp_f32_e32 v225, v89
	v_add_f32_e32 v164, v224, v164
	v_cvt_pk_bf16_f32 v209, v224, v225
	v_add_f32_e32 v164, v225, v164
	s_waitcnt lgkmcnt(3)
	v_mfma_f32_32x32x16_bf16 v[34:49], v[190:193], v[118:121], v[34:49]
	ds_read_b128 v[186:189], v229 offset:26720
	v_exp_f32_e32 v222, v90
	v_exp_f32_e32 v223, v91
	v_add_f32_e32 v164, v222, v164
	v_cvt_pk_bf16_f32 v210, v222, v223
	v_add_f32_e32 v164, v223, v164
	s_waitcnt lgkmcnt(3)
	v_mfma_f32_32x32x16_bf16 v[50:65], v[194:197], v[118:121], v[50:65]
	ds_read_b128 v[190:193], v229 offset:33376
	v_exp_f32_e32 v224, v92
	v_exp_f32_e32 v225, v93
	v_add_f32_e32 v164, v224, v164
	v_cvt_pk_bf16_f32 v211, v224, v225
	v_add_f32_e32 v164, v225, v164
	s_waitcnt lgkmcnt(3)
	v_mfma_f32_32x32x16_bf16 v[34:49], v[198:201], v[122:125], v[34:49]
	ds_read_b128 v[194:197], v229 offset:26752
	v_exp_f32_e32 v222, v94
	v_exp_f32_e32 v223, v95
	v_add_f32_e32 v164, v222, v164
	v_cvt_pk_bf16_f32 v212, v222, v223
	v_add_f32_e32 v164, v223, v164
	s_waitcnt lgkmcnt(3)
	v_mfma_f32_32x32x16_bf16 v[50:65], v[182:185], v[122:125], v[50:65]
	ds_read_b128 v[198:201], v229 offset:33408
	v_exp_f32_e32 v224, v96
	v_exp_f32_e32 v225, v97
	v_add_f32_e32 v164, v224, v164
	v_cvt_pk_bf16_f32 v213, v224, v225
	v_add_f32_e32 v164, v225, v164
	s_waitcnt lgkmcnt(3)
	v_mfma_f32_32x32x16_bf16 v[34:49], v[186:189], v[126:129], v[34:49]
	ds_read_b128 v[182:185], v229 offset:26784
	v_exp_f32_e32 v222, v98
	v_exp_f32_e32 v223, v99
	v_add_f32_e32 v164, v222, v164
	v_cvt_pk_bf16_f32 v214, v222, v223
	v_add_f32_e32 v164, v223, v164
	s_waitcnt lgkmcnt(3)
	v_mfma_f32_32x32x16_bf16 v[50:65], v[190:193], v[126:129], v[50:65]
	ds_read_b128 v[186:189], v229 offset:33440
	v_exp_f32_e32 v224, v100
	v_exp_f32_e32 v225, v101
	v_add_f32_e32 v164, v224, v164
	v_cvt_pk_bf16_f32 v215, v224, v225
	v_add_f32_e32 v164, v225, v164
	s_waitcnt lgkmcnt(3)
	v_mfma_f32_32x32x16_bf16 v[34:49], v[194:197], v[130:133], v[34:49]
	ds_read_b128 v[190:193], v228 offset:35840
	v_exp_f32_e32 v222, v102
	v_exp_f32_e32 v223, v103
	v_add_f32_e32 v164, v222, v164
	v_cvt_pk_bf16_f32 v216, v222, v223
	v_add_f32_e32 v164, v223, v164
	s_waitcnt lgkmcnt(3)
	v_mfma_f32_32x32x16_bf16 v[50:65], v[198:201], v[130:133], v[50:65]
	ds_read_b128 v[194:197], v228 offset:40448
	v_exp_f32_e32 v224, v104
	v_exp_f32_e32 v225, v105
	v_add_f32_e32 v164, v224, v164
	v_cvt_pk_bf16_f32 v217, v224, v225
	v_add_f32_e32 v164, v225, v164
	s_mov_b32 s13, s20
	s_mov_b32 s20, s19
	s_add_i32 s19, s19, 1
	s_cmp_eq_u32 s19, s9
	s_cselect_b32 s19, 0, s19
	s_waitcnt lgkmcnt(3)
	v_mfma_f32_32x32x16_bf16 v[34:49], v[182:185], v[134:137], v[34:49]
	ds_read_b128 v[198:201], v228 offset:35872
	v_exp_f32_e32 v222, v106
	v_exp_f32_e32 v223, v107
	v_add_f32_e32 v164, v222, v164
	v_cvt_pk_bf16_f32 v218, v222, v223
	v_add_f32_e32 v164, v223, v164
	s_waitcnt vmcnt(2)
	ds_write_b128 v172, v[150:153] offset:45056
	v_lshl_add_u32 v222, s19, 17, v178
	global_load_dwordx4 v[150:153], v222, s[52:53]
	s_waitcnt lgkmcnt(4)
	v_mfma_f32_32x32x16_bf16 v[50:65], v[186:189], v[134:137], v[50:65]
	ds_read_b128 v[182:185], v228 offset:40480
	v_exp_f32_e32 v224, v108
	v_exp_f32_e32 v225, v109
	v_add_f32_e32 v164, v224, v164
	v_cvt_pk_bf16_f32 v219, v224, v225
	v_add_f32_e32 v164, v225, v164
	s_and_b64 vcc, exec, s[2:3]
	s_cbranch_vccz .Lmla_p13_nope
	ds_write_b128 v176, v[160:163] offset:45184
	v_lshl_add_u32 v222, s19, 12, v179
	global_load_dwordx4 v[160:163], v222, s[62:63]
.Lmla_p13_nope:
	s_waitcnt lgkmcnt(4)
	v_mfma_f32_32x32x16_bf16 v[2:17], v[190:193], v[206:209], v[2:17]
	ds_read_b128 v[186:189], v228 offset:35904
	v_exp_f32_e32 v222, v110
	v_exp_f32_e32 v223, v111
	v_add_f32_e32 v164, v222, v164
	v_cvt_pk_bf16_f32 v220, v222, v223
	v_add_f32_e32 v164, v223, v164
	v_add_u32_e32 v222, 0xb000, v173
	ds_write_b128 v222, v[202:205] offset:49152
	v_lshl_add_u32 v222, s13, 7, v168
	global_load_dwordx4 v[202:205], v222, s[56:57]
	s_waitcnt lgkmcnt(5)
	v_mfma_f32_32x32x16_bf16 v[18:33], v[194:197], v[206:209], v[18:33]
	ds_read_b128 v[190:193], v228 offset:40512
	v_exp_f32_e32 v224, v112
	v_exp_f32_e32 v225, v113
	v_add_f32_e32 v164, v224, v164
	v_cvt_pk_bf16_f32 v221, v224, v225
	v_add_f32_e32 v164, v225, v164
	s_waitcnt lgkmcnt(5)
	v_mfma_f32_32x32x16_bf16 v[2:17], v[198:201], v[210:213], v[2:17]
	ds_read_b128 v[194:197], v228 offset:35936
	v_max3_f32 v224, v34, v35, v36
	v_max3_f32 v225, v50, v51, v52
	v_max3_f32 v224, v224, v37, v38
	v_max3_f32 v225, v225, v53, v54
	s_waitcnt lgkmcnt(4)
	v_mfma_f32_32x32x16_bf16 v[18:33], v[182:185], v[210:213], v[18:33]
	ds_read_b128 v[198:201], v228 offset:40544
	ds_read_b128 v[182:185], v174
	v_max3_f32 v224, v224, v39, v40
	v_max3_f32 v225, v225, v55, v56
	v_max3_f32 v224, v224, v41, v42
	v_max3_f32 v225, v225, v57, v58
	s_waitcnt lgkmcnt(5)
	v_mfma_f32_32x32x16_bf16 v[2:17], v[186:189], v[214:217], v[2:17]
	ds_read_b128 v[186:189], v174 offset:6656
	v_max3_f32 v224, v224, v43, v44
	v_max3_f32 v225, v225, v59, v60
	v_max3_f32 v224, v224, v45, v46
	v_max3_f32 v225, v225, v61, v62
	s_waitcnt lgkmcnt(4)
	v_mfma_f32_32x32x16_bf16 v[18:33], v[190:193], v[214:217], v[18:33]
	ds_read_b128 v[190:193], v174 offset:32
	v_max3_f32 v224, v224, v47, v48
	v_max3_f32 v225, v225, v63, v64
	v_max3_f32 v224, v224, v49, v65
	v_max_f32_e32 v224, v224, v225
	s_waitcnt lgkmcnt(4)
	v_mfma_f32_32x32x16_bf16 v[2:17], v[194:197], v[218:221], v[2:17]
	ds_read_b128 v[194:197], v174 offset:6688
	v_mov_b32_e32 v225, v224
	v_add_f32_e32 v1, v1, v164
	s_add_i32 s11, s11, 1
	v_permlane32_swap_b32_e32 v224, v225
	s_cmp_eq_u32 s9, s11
	v_max_f32_e32 v167, v224, v225
	v_cmp_lt_f32_e32 vcc, s66, v167
	s_waitcnt lgkmcnt(4)
	v_mfma_f32_32x32x16_bf16 v[18:33], v[198:201], v[218:221], v[18:33]
	s_waitcnt lgkmcnt(7)
	s_barrier

; template <int VAR>
; __device__ __forceinline__ void attn_phase(LAS unsigned char* lds, const AttnP P, int vcu, int G, int wave_s) {
;     ...
;                 if (ND0 == 6) {
;                     KR1(0); KR1(1); KR1(2); KR1(3); SB();
;                     QK1(0, negm); EX2(pc0, 0, w0.x); KR1(4); SB();
;                     QK1(1, negm); EX2(pc0, 2, w0.y); KR1(5); SB();
;                     QK1(2, pn0); EX2(pc0, 4, w0.z); KR1(6); SB();
;                     QK1(3, pn1); EX2(pc0, 6, w0.w); KR1(7); SB();
;                     QK1(4, pn0); EX2(pc0, 8, w1.x); KR1(8); SB();
;                     QK1(5, pn1); EX2(pc0, 10, w1.y); KR1(9); SB();
;                     QK1(6, pn0); EX2(pc0, 12, w1.z); KR1(10); SB();
;                     QK1(7, pn1); EX2(pc0, 14, w1.w); KR1(11); SB();
;                     QK1(8, pn0); EX2(pc1, 0, w2.x); VR1(0); SB();
;                     QK1(9, pn1); EX2(pc1, 2, w2.y); VR1(1); SB();
;                     QK1(10, pn0); EX2(pc1, 4, w2.z); VR1(2); SB();
;                     QK1(11, pn1); EX2(pc1, 6, w2.w); VR1(3); SB();
;                 } else {
;                     KR1(0); KR1(1); KR1(2); KR1(3); SB();
;                     QK1(0, negm); EX2(pc0, 0, w0.x); EX2(pc0, 2, w0.y); KR1(4); SB();
;                     QK1(1, negm); EX2(pc0, 4, w0.z); EX2(pc0, 6, w0.w); KR1(5); SB();
;                     QK1(2, pn0); EX2(pc0, 8, w1.x); EX2(pc0, 10, w1.y); KR1(6); SB();
;                     QK1(3, pn1); EX2(pc0, 12, w1.z); EX2(pc0, 14, w1.w); KR1(7); SB();
;                     QK1(4, pn0); EX2(pc1, 0, w2.x); VR1(0); SB();
;                     QK1(5, pn1); EX2(pc1, 2, w2.y); VR1(1); SB();
;                     QK1(6, pn0); EX2(pc1, 4, w2.z); VR1(2); SB();
;                     QK1(7, pn1); EX2(pc1, 6, w2.w); VR1(3); SB();
;                 }
;                 PV1(0, w0); EX2(pc1, 8, w3.x); VR1(4); SB();
;                 PV1(1, w0); EX2(pc1, 10, w3.y); VR1(5); SB();
;                 PV1(2, w1); EX2(pc1, 12, w3.z); VR1(6); SB();
;                 PV1(3, w1); EX2(pc1, 14, w3.w); VR1(7); SB();
;                 lrun += sacc;
;                 PV1(4, w2); MASK_TILE(pn0, pn1, t + 1); SB();
;                 PV1(5, w2); SB();
;                 PV1(6, w3); SB();
;                 PV1(7, w3); rmn = rowmax32(pn0, pn1); if (!USE_NEGM) rmn -= mref; SB();
;     ...
;             if (hn) { STOREK(t & 1); STOREV((t + 1) & 1); }
;             __syncthreads();
.Lmla_p15_go:
	v_exp_f32_e32 v222, v82
	v_exp_f32_e32 v223, v83
	v_add_f32_e32 v164, 0, v222
	v_cvt_pk_bf16_f32 v206, v222, v223
	v_add_f32_e32 v164, v223, v164
	v_exp_f32_e32 v224, v84
	v_exp_f32_e32 v225, v85
	v_add_f32_e32 v164, v224, v164
	v_cvt_pk_bf16_f32 v207, v224, v225
	v_add_f32_e32 v164, v225, v164
	s_waitcnt lgkmcnt(4)
	v_mfma_f32_32x32x16_bf16 v[34:49], v[182:185], v[114:117], v[66:81]
	ds_read_b128 v[198:201], v174 offset:22592
	v_exp_f32_e32 v222, v86
	v_exp_f32_e32 v223, v87
	v_add_f32_e32 v164, v222, v164
	v_cvt_pk_bf16_f32 v208, v222, v223
	v_add_f32_e32 v164, v223, v164
	s_waitcnt lgkmcnt(4)
	v_mfma_f32_32x32x16_bf16 v[50:65], v[186:189], v[114:117], v[66:81]
	ds_read_b128 v[182:185], v174 offset:29248
	v_exp_f32_e32 v224, v88
	v_exp_f32_e32 v225, v89
	v_add_f32_e32 v164, v224, v164
	v_cvt_pk_bf16_f32 v209, v224, v225
	v_add_f32_e32 v164, v225, v164
	s_waitcnt lgkmcnt(3)
	v_mfma_f32_32x32x16_bf16 v[34:49], v[190:193], v[118:121], v[34:49]
	ds_read_b128 v[186:189], v174 offset:22624
	v_exp_f32_e32 v222, v90
	v_exp_f32_e32 v223, v91
	v_add_f32_e32 v164, v222, v164
	v_cvt_pk_bf16_f32 v210, v222, v223
	v_add_f32_e32 v164, v223, v164
	s_waitcnt lgkmcnt(3)
	v_mfma_f32_32x32x16_bf16 v[50:65], v[194:197], v[118:121], v[50:65]
	ds_read_b128 v[190:193], v174 offset:29280
	v_exp_f32_e32 v224, v92
	v_exp_f32_e32 v225, v93
	v_add_f32_e32 v164, v224, v164
	v_cvt_pk_bf16_f32 v211, v224, v225
	v_add_f32_e32 v164, v225, v164
	s_waitcnt lgkmcnt(3)
	v_mfma_f32_32x32x16_bf16 v[34:49], v[198:201], v[122:125], v[34:49]
	ds_read_b128 v[194:197], v174 offset:22656
	v_exp_f32_e32 v222, v94
	v_exp_f32_e32 v223, v95
	v_add_f32_e32 v164, v222, v164
	v_cvt_pk_bf16_f32 v212, v222, v223
	v_add_f32_e32 v164, v223, v164
	s_waitcnt lgkmcnt(3)
	v_mfma_f32_32x32x16_bf16 v[50:65], v[182:185], v[122:125], v[50:65]
	ds_read_b128 v[198:201], v174 offset:29312
	v_exp_f32_e32 v224, v96
	v_exp_f32_e32 v225, v97
	v_add_f32_e32 v164, v224, v164
	v_cvt_pk_bf16_f32 v213, v224, v225
	v_add_f32_e32 v164, v225, v164
	s_waitcnt lgkmcnt(3)
	v_mfma_f32_32x32x16_bf16 v[34:49], v[186:189], v[126:129], v[34:49]
	ds_read_b128 v[182:185], v174 offset:22688
	v_exp_f32_e32 v222, v98
	v_exp_f32_e32 v223, v99
	v_add_f32_e32 v164, v222, v164
	v_cvt_pk_bf16_f32 v214, v222, v223
	v_add_f32_e32 v164, v223, v164
	s_waitcnt lgkmcnt(3)
	v_mfma_f32_32x32x16_bf16 v[50:65], v[190:193], v[126:129], v[50:65]
	ds_read_b128 v[186:189], v174 offset:29344
	v_exp_f32_e32 v224, v100
	v_exp_f32_e32 v225, v101
	v_add_f32_e32 v164, v224, v164
	v_cvt_pk_bf16_f32 v215, v224, v225
	v_add_f32_e32 v164, v225, v164
	s_waitcnt lgkmcnt(3)
	v_mfma_f32_32x32x16_bf16 v[34:49], v[194:197], v[130:133], v[34:49]
	ds_read_b128 v[190:193], v181 offset:49152
	v_exp_f32_e32 v222, v102
	v_exp_f32_e32 v223, v103
	v_add_f32_e32 v164, v222, v164
	v_cvt_pk_bf16_f32 v216, v222, v223
	v_add_f32_e32 v164, v223, v164
	s_waitcnt lgkmcnt(3)
	v_mfma_f32_32x32x16_bf16 v[50:65], v[198:201], v[130:133], v[50:65]
	ds_read_b128 v[194:197], v181 offset:53760
	v_exp_f32_e32 v224, v104
	v_exp_f32_e32 v225, v105
	v_add_f32_e32 v164, v224, v164
	v_cvt_pk_bf16_f32 v217, v224, v225
	v_add_f32_e32 v164, v225, v164
	s_mov_b32 s13, s20
	s_mov_b32 s20, s19
	s_add_i32 s19, s19, 1
	s_cmp_eq_u32 s19, s9
	s_cselect_b32 s19, 0, s19
	s_waitcnt lgkmcnt(3)
	v_mfma_f32_32x32x16_bf16 v[34:49], v[182:185], v[134:137], v[34:49]
	ds_read_b128 v[198:201], v181 offset:49184
	v_exp_f32_e32 v222, v106
	v_exp_f32_e32 v223, v107
	v_add_f32_e32 v164, v222, v164
	v_cvt_pk_bf16_f32 v218, v222, v223
	v_add_f32_e32 v164, v223, v164
	s_waitcnt vmcnt(2)
	v_add_u32_e32 v222, 0xb000, v172
	ds_write_b128 v222, v[150:153] offset:26624
	v_lshl_add_u32 v222, s19, 17, v178
	global_load_dwordx4 v[150:153], v222, s[52:53]
	s_waitcnt lgkmcnt(4)
	v_mfma_f32_32x32x16_bf16 v[50:65], v[186:189], v[134:137], v[50:65]
	ds_read_b128 v[182:185], v181 offset:53792
	v_exp_f32_e32 v224, v108
	v_exp_f32_e32 v225, v109
	v_add_f32_e32 v164, v224, v164
	v_cvt_pk_bf16_f32 v219, v224, v225
	v_add_f32_e32 v164, v225, v164
	s_and_b64 vcc, exec, s[2:3]
	s_cbranch_vccz .Lmla_p15_nope
	v_add_u32_e32 v222, 0xb000, v176
	ds_write_b128 v222, v[160:163] offset:26752
	v_lshl_add_u32 v222, s19, 12, v179
	global_load_dwordx4 v[160:163], v222, s[62:63]
.Lmla_p15_nope:
	s_waitcnt lgkmcnt(4)
	v_mfma_f32_32x32x16_bf16 v[2:17], v[190:193], v[206:209], v[2:17]
	ds_read_b128 v[186:189], v181 offset:49216
	v_exp_f32_e32 v222, v110
	v_exp_f32_e32 v223, v111
	v_add_f32_e32 v164, v222, v164
	v_cvt_pk_bf16_f32 v220, v222, v223
	v_add_f32_e32 v164, v223, v164
	ds_write_b128 v173, v[202:205] offset:35840
	v_lshl_add_u32 v222, s13, 7, v168
	global_load_dwordx4 v[202:205], v222, s[56:57]
	s_waitcnt lgkmcnt(5)
	v_mfma_f32_32x32x16_bf16 v[18:33], v[194:197], v[206:209], v[18:33]
	ds_read_b128 v[190:193], v181 offset:53824
	v_exp_f32_e32 v224, v112
	v_exp_f32_e32 v225, v113
	v_add_f32_e32 v164, v224, v164
	v_cvt_pk_bf16_f32 v221, v224, v225
	v_add_f32_e32 v164, v225, v164
	s_waitcnt lgkmcnt(5)
	v_mfma_f32_32x32x16_bf16 v[2:17], v[198:201], v[210:213], v[2:17]
	ds_read_b128 v[194:197], v181 offset:49248
	v_max3_f32 v224, v34, v35, v36
	v_max3_f32 v225, v50, v51, v52
	v_max3_f32 v224, v224, v37, v38
	v_max3_f32 v225, v225, v53, v54
	s_waitcnt lgkmcnt(4)
	v_mfma_f32_32x32x16_bf16 v[18:33], v[182:185], v[210:213], v[18:33]
	ds_read_b128 v[198:201], v181 offset:53856
	ds_read_b128 v[182:185], v174 offset:45056
	v_max3_f32 v224, v224, v39, v40
	v_max3_f32 v225, v225, v55, v56
	v_max3_f32 v224, v224, v41, v42
	v_max3_f32 v225, v225, v57, v58
	s_waitcnt lgkmcnt(5)
	v_mfma_f32_32x32x16_bf16 v[2:17], v[186:189], v[214:217], v[2:17]
	ds_read_b128 v[186:189], v174 offset:51712
	v_max3_f32 v224, v224, v43, v44
	v_max3_f32 v225, v225, v59, v60
	v_max3_f32 v224, v224, v45, v46
	v_max3_f32 v225, v225, v61, v62
	s_waitcnt lgkmcnt(4)
	v_mfma_f32_32x32x16_bf16 v[18:33], v[190:193], v[214:217], v[18:33]
	ds_read_b128 v[190:193], v174 offset:45088
	v_max3_f32 v224, v224, v47, v48
	v_max3_f32 v225, v225, v63, v64
	v_max3_f32 v224, v224, v49, v65
	v_max_f32_e32 v224, v224, v225
	s_waitcnt lgkmcnt(4)
	v_mfma_f32_32x32x16_bf16 v[2:17], v[194:197], v[218:221], v[2:17]
	ds_read_b128 v[194:197], v174 offset:51744
	v_mov_b32_e32 v225, v224
	v_add_f32_e32 v1, v1, v164
	s_add_i32 s11, s11, 1
	v_permlane32_swap_b32_e32 v224, v225
	s_cmp_eq_u32 s9, s11
	v_max_f32_e32 v167, v224, v225
	v_cmp_lt_f32_e32 vcc, s66, v167
	s_waitcnt lgkmcnt(4)
	v_mfma_f32_32x32x16_bf16 v[18:33], v[198:201], v[218:221], v[18:33]
	s_waitcnt lgkmcnt(7)
	s_barrier

; template <int VAR>
; __device__ __forceinline__ void attn_phase(LAS unsigned char* lds, const AttnP P, int vcu, int G, int wave_s) {
;     ...
;                 if (ND0 == 6) {
;                     KR1(0); KR1(1); KR1(2); KR1(3); SB();
;                     QK1(0, negm); EX2(pc0, 0, w0.x); KR1(4); SB();
;                     QK1(1, negm); EX2(pc0, 2, w0.y); KR1(5); SB();
;                     QK1(2, pn0); EX2(pc0, 4, w0.z); KR1(6); SB();
;                     QK1(3, pn1); EX2(pc0, 6, w0.w); KR1(7); SB();
;                     QK1(4, pn0); EX2(pc0, 8, w1.x); KR1(8); SB();
;                     QK1(5, pn1); EX2(pc0, 10, w1.y); KR1(9); SB();
;                     QK1(6, pn0); EX2(pc0, 12, w1.z); KR1(10); SB();
;                     QK1(7, pn1); EX2(pc0, 14, w1.w); KR1(11); SB();
;                     QK1(8, pn0); EX2(pc1, 0, w2.x); VR1(0); SB();
;                     QK1(9, pn1); EX2(pc1, 2, w2.y); VR1(1); SB();
;                     QK1(10, pn0); EX2(pc1, 4, w2.z); VR1(2); SB();
;                     QK1(11, pn1); EX2(pc1, 6, w2.w); VR1(3); SB();
;                 } else {
;                     KR1(0); KR1(1); KR1(2); KR1(3); SB();
;                     QK1(0, negm); EX2(pc0, 0, w0.x); EX2(pc0, 2, w0.y); KR1(4); SB();
;                     QK1(1, negm); EX2(pc0, 4, w0.z); EX2(pc0, 6, w0.w); KR1(5); SB();
;                     QK1(2, pn0); EX2(pc0, 8, w1.x); EX2(pc0, 10, w1.y); KR1(6); SB();
;                     QK1(3, pn1); EX2(pc0, 12, w1.z); EX2(pc0, 14, w1.w); KR1(7); SB();
;                     QK1(4, pn0); EX2(pc1, 0, w2.x); VR1(0); SB();
;                     QK1(5, pn1); EX2(pc1, 2, w2.y); VR1(1); SB();
;                     QK1(6, pn0); EX2(pc1, 4, w2.z); VR1(2); SB();
;                     QK1(7, pn1); EX2(pc1, 6, w2.w); VR1(3); SB();
;                 }
;                 PV1(0, w0); EX2(pc1, 8, w3.x); VR1(4); SB();
;                 PV1(1, w0); EX2(pc1, 10, w3.y); VR1(5); SB();
;                 PV1(2, w1); EX2(pc1, 12, w3.z); VR1(6); SB();
;                 PV1(3, w1); EX2(pc1, 14, w3.w); VR1(7); SB();
;                 lrun += sacc;
;                 PV1(4, w2); MASK_TILE(pn0, pn1, t + 1); SB();
;                 PV1(5, w2); SB();
;                 PV1(6, w3); SB();
;                 PV1(7, w3); rmn = rowmax32(pn0, pn1); if (!USE_NEGM) rmn -= mref; SB();
;     ...
;             if (hn) { STOREK(t & 1); STOREV((t + 1) & 1); }
;             __syncthreads();
.Lmla_p17_go:
	v_exp_f32_e32 v222, v82
	v_exp_f32_e32 v223, v83
	v_add_f32_e32 v164, 0, v222
	v_cvt_pk_bf16_f32 v206, v222, v223
	v_add_f32_e32 v164, v223, v164
	v_exp_f32_e32 v224, v84
	v_exp_f32_e32 v225, v85
	v_add_f32_e32 v164, v224, v164
	v_cvt_pk_bf16_f32 v207, v224, v225
	v_add_f32_e32 v164, v225, v164
	s_waitcnt lgkmcnt(4)
	v_mfma_f32_32x32x16_bf16 v[34:49], v[182:185], v[114:117], v[66:81]
	ds_read_b128 v[198:201], v229 offset:13376
	v_exp_f32_e32 v222, v86
	v_exp_f32_e32 v223, v87
	v_add_f32_e32 v164, v222, v164
	v_cvt_pk_bf16_f32 v208, v222, v223
	v_add_f32_e32 v164, v223, v164
	s_waitcnt lgkmcnt(4)
	v_mfma_f32_32x32x16_bf16 v[50:65], v[186:189], v[114:117], v[66:81]
	ds_read_b128 v[182:185], v229 offset:20032
	v_exp_f32_e32 v224, v88
	v_exp_f32_e32 v225, v89
	v_add_f32_e32 v164, v224, v164
	v_cvt_pk_bf16_f32 v209, v224, v225
	v_add_f32_e32 v164, v225, v164
	s_waitcnt lgkmcnt(3)
	v_mfma_f32_32x32x16_bf16 v[34:49], v[190:193], v[118:121], v[34:49]
	ds_read_b128 v[186:189], v229 offset:13408
	v_exp_f32_e32 v222, v90
	v_exp_f32_e32 v223, v91
	v_add_f32_e32 v164, v222, v164
	v_cvt_pk_bf16_f32 v210, v222, v223
	v_add_f32_e32 v164, v223, v164
	s_waitcnt lgkmcnt(3)
	v_mfma_f32_32x32x16_bf16 v[50:65], v[194:197], v[118:121], v[50:65]
	ds_read_b128 v[190:193], v229 offset:20064
	v_exp_f32_e32 v224, v92
	v_exp_f32_e32 v225, v93
	v_add_f32_e32 v164, v224, v164
	v_cvt_pk_bf16_f32 v211, v224, v225
	v_add_f32_e32 v164, v225, v164
	s_waitcnt lgkmcnt(3)
	v_mfma_f32_32x32x16_bf16 v[34:49], v[198:201], v[122:125], v[34:49]
	ds_read_b128 v[194:197], v229 offset:13440
	v_exp_f32_e32 v222, v94
	v_exp_f32_e32 v223, v95
	v_add_f32_e32 v164, v222, v164
	v_cvt_pk_bf16_f32 v212, v222, v223
	v_add_f32_e32 v164, v223, v164
	s_waitcnt lgkmcnt(3)
	v_mfma_f32_32x32x16_bf16 v[50:65], v[182:185], v[122:125], v[50:65]
	ds_read_b128 v[198:201], v229 offset:20096
	v_exp_f32_e32 v224, v96
	v_exp_f32_e32 v225, v97
	v_add_f32_e32 v164, v224, v164
	v_cvt_pk_bf16_f32 v213, v224, v225
	v_add_f32_e32 v164, v225, v164
	s_waitcnt lgkmcnt(3)
	v_mfma_f32_32x32x16_bf16 v[34:49], v[186:189], v[126:129], v[34:49]
	ds_read_b128 v[182:185], v229 offset:13472
	v_exp_f32_e32 v222, v98
	v_exp_f32_e32 v223, v99
	v_add_f32_e32 v164, v222, v164
	v_cvt_pk_bf16_f32 v214, v222, v223
	v_add_f32_e32 v164, v223, v164
	s_waitcnt lgkmcnt(3)
	v_mfma_f32_32x32x16_bf16 v[50:65], v[190:193], v[126:129], v[50:65]
	ds_read_b128 v[186:189], v229 offset:20128
	v_exp_f32_e32 v224, v100
	v_exp_f32_e32 v225, v101
	v_add_f32_e32 v164, v224, v164
	v_cvt_pk_bf16_f32 v215, v224, v225
	v_add_f32_e32 v164, v225, v164
	s_waitcnt lgkmcnt(3)
	v_mfma_f32_32x32x16_bf16 v[34:49], v[194:197], v[130:133], v[34:49]
	ds_read_b128 v[190:193], v228 offset:35840
	v_exp_f32_e32 v222, v102
	v_exp_f32_e32 v223, v103
	v_add_f32_e32 v164, v222, v164
	v_cvt_pk_bf16_f32 v216, v222, v223
	v_add_f32_e32 v164, v223, v164
	s_waitcnt lgkmcnt(3)
	v_mfma_f32_32x32x16_bf16 v[50:65], v[198:201], v[130:133], v[50:65]
	ds_read_b128 v[194:197], v228 offset:40448
	v_exp_f32_e32 v224, v104
	v_exp_f32_e32 v225, v105
	v_add_f32_e32 v164, v224, v164
	v_cvt_pk_bf16_f32 v217, v224, v225
	v_add_f32_e32 v164, v225, v164
	s_mov_b32 s13, s20
	s_mov_b32 s20, s19
	s_add_i32 s19, s19, 1
	s_cmp_eq_u32 s19, s9
	s_cselect_b32 s19, 0, s19
	s_waitcnt lgkmcnt(3)
	v_mfma_f32_32x32x16_bf16 v[34:49], v[182:185], v[134:137], v[34:49]
	ds_read_b128 v[198:201], v228 offset:35872
	v_exp_f32_e32 v222, v106
	v_exp_f32_e32 v223, v107
	v_add_f32_e32 v164, v222, v164
	v_cvt_pk_bf16_f32 v218, v222, v223
	v_add_f32_e32 v164, v223, v164
	s_waitcnt vmcnt(2)
	ds_write_b128 v172, v[150:153] offset:22528
	v_lshl_add_u32 v222, s19, 17, v178
	global_load_dwordx4 v[150:153], v222, s[52:53]
	s_waitcnt lgkmcnt(4)
	v_mfma_f32_32x32x16_bf16 v[50:65], v[186:189], v[134:137], v[50:65]
	ds_read_b128 v[182:185], v228 offset:40480
	v_exp_f32_e32 v224, v108
	v_exp_f32_e32 v225, v109
	v_add_f32_e32 v164, v224, v164
	v_cvt_pk_bf16_f32 v219, v224, v225
	v_add_f32_e32 v164, v225, v164
	s_and_b64 vcc, exec, s[2:3]
	s_cbranch_vccz .Lmla_p17_nope
	ds_write_b128 v176, v[160:163] offset:22656
	v_lshl_add_u32 v222, s19, 12, v179
	global_load_dwordx4 v[160:163], v222, s[62:63]
.Lmla_p17_nope:
	s_waitcnt lgkmcnt(4)
	v_mfma_f32_32x32x16_bf16 v[2:17], v[190:193], v[206:209], v[2:17]
	ds_read_b128 v[186:189], v228 offset:35904
	v_exp_f32_e32 v222, v110
	v_exp_f32_e32 v223, v111
	v_add_f32_e32 v164, v222, v164
	v_cvt_pk_bf16_f32 v220, v222, v223
	v_add_f32_e32 v164, v223, v164
	v_add_u32_e32 v222, 0xb000, v173
	ds_write_b128 v222, v[202:205] offset:49152
	v_lshl_add_u32 v222, s13, 7, v168
	global_load_dwordx4 v[202:205], v222, s[56:57]
	s_waitcnt lgkmcnt(5)
	v_mfma_f32_32x32x16_bf16 v[18:33], v[194:197], v[206:209], v[18:33]
	ds_read_b128 v[190:193], v228 offset:40512
	v_exp_f32_e32 v224, v112
	v_exp_f32_e32 v225, v113
	v_add_f32_e32 v164, v224, v164
	v_cvt_pk_bf16_f32 v221, v224, v225
	v_add_f32_e32 v164, v225, v164
	s_waitcnt lgkmcnt(5)
	v_mfma_f32_32x32x16_bf16 v[2:17], v[198:201], v[210:213], v[2:17]
	ds_read_b128 v[194:197], v228 offset:35936
	v_max3_f32 v224, v34, v35, v36
	v_max3_f32 v225, v50, v51, v52
	v_max3_f32 v224, v224, v37, v38
	v_max3_f32 v225, v225, v53, v54
	s_waitcnt lgkmcnt(4)
	v_mfma_f32_32x32x16_bf16 v[18:33], v[182:185], v[210:213], v[18:33]
	ds_read_b128 v[198:201], v228 offset:40544
	ds_read_b128 v[182:185], v229 offset:26624
	v_max3_f32 v224, v224, v39, v40
	v_max3_f32 v225, v225, v55, v56
	v_max3_f32 v224, v224, v41, v42
	v_max3_f32 v225, v225, v57, v58
	s_waitcnt lgkmcnt(5)
	v_mfma_f32_32x32x16_bf16 v[2:17], v[186:189], v[214:217], v[2:17]
	ds_read_b128 v[186:189], v229 offset:33280
	v_max3_f32 v224, v224, v43, v44
	v_max3_f32 v225, v225, v59, v60
	v_max3_f32 v224, v224, v45, v46
	v_max3_f32 v225, v225, v61, v62
	s_waitcnt lgkmcnt(4)
	v_mfma_f32_32x32x16_bf16 v[18:33], v[190:193], v[214:217], v[18:33]
	ds_read_b128 v[190:193], v229 offset:26656
	v_max3_f32 v224, v224, v47, v48
	v_max3_f32 v225, v225, v63, v64
	v_max3_f32 v224, v224, v49, v65
	v_max_f32_e32 v224, v224, v225
	s_waitcnt lgkmcnt(4)
	v_mfma_f32_32x32x16_bf16 v[2:17], v[194:197], v[218:221], v[2:17]
	ds_read_b128 v[194:197], v229 offset:33312
	v_mov_b32_e32 v225, v224
	v_add_f32_e32 v1, v1, v164
	s_add_i32 s11, s11, 1
	v_permlane32_swap_b32_e32 v224, v225
	s_cmp_eq_u32 s9, s11
	v_max_f32_e32 v167, v224, v225
	v_cmp_lt_f32_e32 vcc, s66, v167
	s_waitcnt lgkmcnt(4)
	v_mfma_f32_32x32x16_bf16 v[18:33], v[198:201], v[218:221], v[18:33]
	s_waitcnt lgkmcnt(7)
	s_barrier

; template <int VAR>
; __device__ __forceinline__ void attn_phase(LAS unsigned char* lds, const AttnP P, int vcu, int G, int wave_s) {
;     ...
;                 if (ND0 == 6) {
;                     KR1(0); KR1(1); KR1(2); KR1(3); SB();
;                     QK1(0, negm); EX2(pc0, 0, w0.x); KR1(4); SB();
;                     QK1(1, negm); EX2(pc0, 2, w0.y); KR1(5); SB();
;                     QK1(2, pn0); EX2(pc0, 4, w0.z); KR1(6); SB();
;                     QK1(3, pn1); EX2(pc0, 6, w0.w); KR1(7); SB();
;                     QK1(4, pn0); EX2(pc0, 8, w1.x); KR1(8); SB();
;                     QK1(5, pn1); EX2(pc0, 10, w1.y); KR1(9); SB();
;                     QK1(6, pn0); EX2(pc0, 12, w1.z); KR1(10); SB();
;                     QK1(7, pn1); EX2(pc0, 14, w1.w); KR1(11); SB();
;                     QK1(8, pn0); EX2(pc1, 0, w2.x); VR1(0); SB();
;                     QK1(9, pn1); EX2(pc1, 2, w2.y); VR1(1); SB();
;                     QK1(10, pn0); EX2(pc1, 4, w2.z); VR1(2); SB();
;                     QK1(11, pn1); EX2(pc1, 6, w2.w); VR1(3); SB();
;                 } else {
;                     KR1(0); KR1(1); KR1(2); KR1(3); SB();
;                     QK1(0, negm); EX2(pc0, 0, w0.x); EX2(pc0, 2, w0.y); KR1(4); SB();
;                     QK1(1, negm); EX2(pc0, 4, w0.z); EX2(pc0, 6, w0.w); KR1(5); SB();
;                     QK1(2, pn0); EX2(pc0, 8, w1.x); EX2(pc0, 10, w1.y); KR1(6); SB();
;                     QK1(3, pn1); EX2(pc0, 12, w1.z); EX2(pc0, 14, w1.w); KR1(7); SB();
;                     QK1(4, pn0); EX2(pc1, 0, w2.x); VR1(0); SB();
;                     QK1(5, pn1); EX2(pc1, 2, w2.y); VR1(1); SB();
;                     QK1(6, pn0); EX2(pc1, 4, w2.z); VR1(2); SB();
;                     QK1(7, pn1); EX2(pc1, 6, w2.w); VR1(3); SB();
;                 }
;                 PV1(0, w0); EX2(pc1, 8, w3.x); VR1(4); SB();
;                 PV1(1, w0); EX2(pc1, 10, w3.y); VR1(5); SB();
;                 PV1(2, w1); EX2(pc1, 12, w3.z); VR1(6); SB();
;                 PV1(3, w1); EX2(pc1, 14, w3.w); VR1(7); SB();
;                 lrun += sacc;
;                 PV1(4, w2); MASK_TILE(pn0, pn1, t + 1); SB();
;                 PV1(5, w2); SB();
;                 PV1(6, w3); SB();
;                 PV1(7, w3); rmn = rowmax32(pn0, pn1); if (!USE_NEGM) rmn -= mref; SB();
;     ...
;             if (hn) { STOREK(t & 1); STOREV((t + 1) & 1); }
;             __syncthreads();
.Lmla_p19_go:
	v_exp_f32_e32 v222, v82
	v_exp_f32_e32 v223, v83
	v_add_f32_e32 v164, 0, v222
	v_cvt_pk_bf16_f32 v206, v222, v223
	v_add_f32_e32 v164, v223, v164
	v_exp_f32_e32 v224, v84
	v_exp_f32_e32 v225, v85
	v_add_f32_e32 v164, v224, v164
	v_cvt_pk_bf16_f32 v207, v224, v225
	v_add_f32_e32 v164, v225, v164
	s_waitcnt lgkmcnt(4)
	v_mfma_f32_32x32x16_bf16 v[34:49], v[182:185], v[114:117], v[66:81]
	ds_read_b128 v[198:201], v174 offset:64
	v_exp_f32_e32 v222, v86
	v_exp_f32_e32 v223, v87
	v_add_f32_e32 v164, v222, v164
	v_cvt_pk_bf16_f32 v208, v222, v223
	v_add_f32_e32 v164, v223, v164
	s_waitcnt lgkmcnt(4)
	v_mfma_f32_32x32x16_bf16 v[50:65], v[186:189], v[114:117], v[66:81]
	ds_read_b128 v[182:185], v174 offset:6720
	v_exp_f32_e32 v224, v88
	v_exp_f32_e32 v225, v89
	v_add_f32_e32 v164, v224, v164
	v_cvt_pk_bf16_f32 v209, v224, v225
	v_add_f32_e32 v164, v225, v164
	s_waitcnt lgkmcnt(3)
	v_mfma_f32_32x32x16_bf16 v[34:49], v[190:193], v[118:121], v[34:49]
	ds_read_b128 v[186:189], v174 offset:96
	v_exp_f32_e32 v222, v90
	v_exp_f32_e32 v223, v91
	v_add_f32_e32 v164, v222, v164
	v_cvt_pk_bf16_f32 v210, v222, v223
	v_add_f32_e32 v164, v223, v164
	s_waitcnt lgkmcnt(3)
	v_mfma_f32_32x32x16_bf16 v[50:65], v[194:197], v[118:121], v[50:65]
	ds_read_b128 v[190:193], v174 offset:6752
	v_exp_f32_e32 v224, v92
	v_exp_f32_e32 v225, v93
	v_add_f32_e32 v164, v224, v164
	v_cvt_pk_bf16_f32 v211, v224, v225
	v_add_f32_e32 v164, v225, v164
	s_waitcnt lgkmcnt(3)
	v_mfma_f32_32x32x16_bf16 v[34:49], v[198:201], v[122:125], v[34:49]
	ds_read_b128 v[194:197], v174 offset:128
	v_exp_f32_e32 v222, v94
	v_exp_f32_e32 v223, v95
	v_add_f32_e32 v164, v222, v164
	v_cvt_pk_bf16_f32 v212, v222, v223
	v_add_f32_e32 v164, v223, v164
	s_waitcnt lgkmcnt(3)
	v_mfma_f32_32x32x16_bf16 v[50:65], v[182:185], v[122:125], v[50:65]
	ds_read_b128 v[198:201], v174 offset:6784
	v_exp_f32_e32 v224, v96
	v_exp_f32_e32 v225, v97
	v_add_f32_e32 v164, v224, v164
	v_cvt_pk_bf16_f32 v213, v224, v225
	v_add_f32_e32 v164, v225, v164
	s_waitcnt lgkmcnt(3)
	v_mfma_f32_32x32x16_bf16 v[34:49], v[186:189], v[126:129], v[34:49]
	ds_read_b128 v[182:185], v174 offset:160
	v_exp_f32_e32 v222, v98
	v_exp_f32_e32 v223, v99
	v_add_f32_e32 v164, v222, v164
	v_cvt_pk_bf16_f32 v214, v222, v223
	v_add_f32_e32 v164, v223, v164
	s_waitcnt lgkmcnt(3)
	v_mfma_f32_32x32x16_bf16 v[50:65], v[190:193], v[126:129], v[50:65]
	ds_read_b128 v[186:189], v174 offset:6816
	v_exp_f32_e32 v224, v100
	v_exp_f32_e32 v225, v101
	v_add_f32_e32 v164, v224, v164
	v_cvt_pk_bf16_f32 v215, v224, v225
	v_add_f32_e32 v164, v225, v164
	s_waitcnt lgkmcnt(3)
	v_mfma_f32_32x32x16_bf16 v[34:49], v[194:197], v[130:133], v[34:49]
	ds_read_b128 v[190:193], v181 offset:49152
	v_exp_f32_e32 v222, v102
	v_exp_f32_e32 v223, v103
	v_add_f32_e32 v164, v222, v164
	v_cvt_pk_bf16_f32 v216, v222, v223
	v_add_f32_e32 v164, v223, v164
	s_waitcnt lgkmcnt(3)
	v_mfma_f32_32x32x16_bf16 v[50:65], v[198:201], v[130:133], v[50:65]
	ds_read_b128 v[194:197], v181 offset:53760
	v_exp_f32_e32 v224, v104
	v_exp_f32_e32 v225, v105
	v_add_f32_e32 v164, v224, v164
	v_cvt_pk_bf16_f32 v217, v224, v225
	v_add_f32_e32 v164, v225, v164
	s_mov_b32 s13, s20
	s_mov_b32 s20, s19
	s_add_i32 s19, s19, 1
	s_cmp_eq_u32 s19, s9
	s_cselect_b32 s19, 0, s19
	s_waitcnt lgkmcnt(3)
	v_mfma_f32_32x32x16_bf16 v[34:49], v[182:185], v[134:137], v[34:49]
	ds_read_b128 v[198:201], v181 offset:49184
	v_exp_f32_e32 v222, v106
	v_exp_f32_e32 v223, v107
	v_add_f32_e32 v164, v222, v164
	v_cvt_pk_bf16_f32 v218, v222, v223
	v_add_f32_e32 v164, v223, v164
	s_waitcnt vmcnt(2)
	ds_write_b128 v172, v[150:153] offset:58368
	v_lshl_add_u32 v222, s19, 17, v178
	global_load_dwordx4 v[150:153], v222, s[52:53]
	s_waitcnt lgkmcnt(4)
	v_mfma_f32_32x32x16_bf16 v[50:65], v[186:189], v[134:137], v[50:65]
	ds_read_b128 v[182:185], v181 offset:53792
	v_exp_f32_e32 v224, v108
	v_exp_f32_e32 v225, v109
	v_add_f32_e32 v164, v224, v164
	v_cvt_pk_bf16_f32 v219, v224, v225
	v_add_f32_e32 v164, v225, v164
	s_and_b64 vcc, exec, s[2:3]
	s_cbranch_vccz .Lmla_p19_nope
	ds_write_b128 v176, v[160:163] offset:58496
	v_lshl_add_u32 v222, s19, 12, v179
	global_load_dwordx4 v[160:163], v222, s[62:63]
.Lmla_p19_nope:
	s_waitcnt lgkmcnt(4)
	v_mfma_f32_32x32x16_bf16 v[2:17], v[190:193], v[206:209], v[2:17]
	ds_read_b128 v[186:189], v181 offset:49216
	v_exp_f32_e32 v222, v110
	v_exp_f32_e32 v223, v111
	v_add_f32_e32 v164, v222, v164
	v_cvt_pk_bf16_f32 v220, v222, v223
	v_add_f32_e32 v164, v223, v164
	ds_write_b128 v173, v[202:205] offset:35840
	v_lshl_add_u32 v222, s13, 7, v168
	global_load_dwordx4 v[202:205], v222, s[56:57]
	s_waitcnt lgkmcnt(5)
	v_mfma_f32_32x32x16_bf16 v[18:33], v[194:197], v[206:209], v[18:33]
	ds_read_b128 v[190:193], v181 offset:53824
	v_exp_f32_e32 v224, v112
	v_exp_f32_e32 v225, v113
	v_add_f32_e32 v164, v224, v164
	v_cvt_pk_bf16_f32 v221, v224, v225
	v_add_f32_e32 v164, v225, v164
	s_waitcnt lgkmcnt(5)
	v_mfma_f32_32x32x16_bf16 v[2:17], v[198:201], v[210:213], v[2:17]
	ds_read_b128 v[194:197], v181 offset:49248
	v_max3_f32 v224, v34, v35, v36
	v_max3_f32 v225, v50, v51, v52
	v_max3_f32 v224, v224, v37, v38
	v_max3_f32 v225, v225, v53, v54
	s_waitcnt lgkmcnt(4)
	v_mfma_f32_32x32x16_bf16 v[18:33], v[182:185], v[210:213], v[18:33]
	ds_read_b128 v[198:201], v181 offset:53856
	ds_read_b128 v[182:185], v174 offset:22528
	v_max3_f32 v224, v224, v39, v40
	v_max3_f32 v225, v225, v55, v56
	v_max3_f32 v224, v224, v41, v42
	v_max3_f32 v225, v225, v57, v58
	s_waitcnt lgkmcnt(5)
	v_mfma_f32_32x32x16_bf16 v[2:17], v[186:189], v[214:217], v[2:17]
	ds_read_b128 v[186:189], v174 offset:29184
	v_max3_f32 v224, v224, v43, v44
	v_max3_f32 v225, v225, v59, v60
	v_max3_f32 v224, v224, v45, v46
	v_max3_f32 v225, v225, v61, v62
	s_waitcnt lgkmcnt(4)
	v_mfma_f32_32x32x16_bf16 v[18:33], v[190:193], v[214:217], v[18:33]
	ds_read_b128 v[190:193], v174 offset:22560
	v_max3_f32 v224, v224, v47, v48
	v_max3_f32 v225, v225, v63, v64
	v_max3_f32 v224, v224, v49, v65
	v_max_f32_e32 v224, v224, v225
	s_waitcnt lgkmcnt(4)
	v_mfma_f32_32x32x16_bf16 v[2:17], v[194:197], v[218:221], v[2:17]
	ds_read_b128 v[194:197], v174 offset:29216
	v_mov_b32_e32 v225, v224
	v_add_f32_e32 v1, v1, v164
	s_add_i32 s11, s11, 1
	v_permlane32_swap_b32_e32 v224, v225
	s_cmp_eq_u32 s9, s11
	v_max_f32_e32 v167, v224, v225
	v_cmp_lt_f32_e32 vcc, s66, v167
	s_waitcnt lgkmcnt(4)
	v_mfma_f32_32x32x16_bf16 v[18:33], v[198:201], v[218:221], v[18:33]
	s_waitcnt lgkmcnt(7)
	s_barrier
	s_branch .Lmla_p0
